# GEMM K-loops: 4 of the 6 LDS-DMA pieces of each SP2 phase are issued between the MFMAs of the following block; SP2 wait vmcnt(4)
# speedup vs baseline: 1.0100x; 1.0100x over previous
; #define PG8_STAGE(bufoff, gbase, voff) do { _Pragma("unroll") for (int _i = 0; _i < 2; ++_i) \
;         __builtin_amdgcn_global_load_lds((const unsigned*)((const char*)(gbase) + (voff)[_i]), (LAS unsigned*)(lds + (bufoff) + ldsw + _i * 8192), 16, 0, 0); } while (0)
; #define PG8_LDA(dst, b, h) do { _Pragma("unroll") for (int m = 0; m < 4; ++m) _Pragma("unroll") for (int k = 0; k < 2; ++k) dst[m][k] = *(const LAS bf16x8*)(lds + PG8_SA(b, h) + aoff + m * 2048 + k * 1024); } while (0)
; #define PG8_LDB(dst, b, h) do { _Pragma("unroll") for (int n = 0; n < 2; ++n) _Pragma("unroll") for (int k = 0; k < 2; ++k) dst[n][k] = *(const LAS bf16x8*)(lds + PG8_SB(b, h) + boff + n * 2048 + k * 1024); } while (0)
; #define PG8_MMA(ai, bj, At, Bt) do { __builtin_amdgcn_s_setprio(1); _Pragma("unroll") for (int m = 0; m < 4; ++m) _Pragma("unroll") for (int n = 0; n < 2; ++n) _Pragma("unroll") for (int k = 0; k < 2; ++k) \
;         acc[ai][bj][m][n] = __builtin_amdgcn_mfma_f32_16x16x32_bf16(Bt[n][k], At[m][k], acc[ai][bj][m][n], 0, 0, 0); __builtin_amdgcn_s_setprio(0); } while (0)
; #define PG8_WAIT_V(n) asm volatile("s_waitcnt vmcnt(" #n ")" ::: "memory")
; #define PG8_WAIT_L(n) asm volatile("s_waitcnt lgkmcnt(" #n ")" ::: "memory")
; #define PG8_BAR __builtin_amdgcn_s_barrier()
; #define PG8_SCHED __builtin_amdgcn_sched_barrier(0)
; template <class Epi, class Sched, bool ALIGN_EPI = false, bool SP2 = false>
; __device__ __forceinline__ void gemm_phase(LAS unsigned char* lds, const Gemm g, const Sched& S, const Epi& E) {
;     ...
;             PG8_LDB(B0, 0, 0); PG8_LDB(B1, 0, 1); PG8_SCHED; PG8_LDA(At, 0, 0); PG8_STAGE(PG8_SA(1, 1), a1 + hstep, voffA);
;             PG8_WAIT_V(8); PG8_WAIT_L(0); PG8_BAR; PG8_MMA(0, 0, At, B0); PG8_MMA(0, 1, At, B1); PG8_BAR; PG8_SCHED;
;             PG8_LDA(At, 0, 1); PG8_STAGE(PG8_SB(0, 0), b2, voffB); PG8_STAGE(PG8_SB(0, 1), b2 + hstep, voffB); PG8_STAGE(PG8_SA(0, 0), a2, voffA);
;             PG8_WAIT_V(8); PG8_WAIT_L(0); PG8_BAR; PG8_MMA(1, 0, At, B0); PG8_MMA(1, 1, At, B1); PG8_BAR; PG8_SCHED;
.LBB0_122:
	s_add_u32 s14, s42, 0xfffc0080
	s_addc_u32 s15, s43, -1
	s_add_i32 vcc_hi, 0, 0x10000
	s_cmp_eq_u32 vcc_lo, 12
	s_cselect_b32 s97, s45, s15
	s_cselect_b32 s96, s51, s14
	s_cselect_b32 s47, s65, s99
	s_cselect_b32 s46, s76, s98
	s_add_i32 s16, 0, 0x14000
	v_add_u32_e32 v140, vcc_hi, v192
	v_add_u32_e32 v152, s16, v192
	s_waitcnt lgkmcnt(0)
	ds_read_b128 v[128:131], v140
	ds_read_b128 v[132:135], v140 offset:1024
	ds_read_b128 v[136:139], v140 offset:2048
	ds_read_b128 v[140:143], v140 offset:3072
	ds_read_b128 v[144:147], v152
	ds_read_b128 v[148:151], v152 offset:1024
	ds_read_b128 v[180:183], v152 offset:2048
	ds_read_b128 v[184:187], v152 offset:3072
	v_lshl_add_u64 v[204:205], s[42:43], 0, v[176:177]
	s_add_i32 m0, s93, 0xc000
	ds_read_b128 v[188:191], v194
	ds_read_b128 v[196:199], v194 offset:1024
	ds_read_b128 v[200:203], v194 offset:2048
	ds_read_b128 v[218:221], v194 offset:3072
	ds_read_b128 v[222:225], v194 offset:4096
	ds_read_b128 v[226:229], v194 offset:5120
	ds_read_b128 v[230:233], v194 offset:6144
	ds_read_b128 v[234:237], v194 offset:7168
	global_load_lds_dwordx4 v[204:205], off
	v_lshl_add_u64 v[204:205], s[42:43], 0, v[178:179]
	s_add_i32 m0, s93, 0xe000
	s_nop 0
	global_load_lds_dwordx4 v[204:205], off
	s_waitcnt vmcnt(8)
	s_waitcnt lgkmcnt(0)
	s_barrier
	s_setprio 1
	s_waitcnt lgkmcnt(0)
	v_mfma_f32_16x16x32_bf16 v[116:119], v[128:131], v[188:191], v[116:119]
	v_mfma_f32_16x16x32_bf16 v[112:115], v[136:139], v[188:191], v[112:115]
	v_mfma_f32_16x16x32_bf16 v[100:103], v[128:131], v[200:203], v[100:103]
	v_mfma_f32_16x16x32_bf16 v[96:99], v[136:139], v[200:203], v[96:99]
	v_mfma_f32_16x16x32_bf16 v[84:87], v[128:131], v[222:225], v[84:87]
	v_mfma_f32_16x16x32_bf16 v[80:83], v[136:139], v[222:225], v[80:83]
	v_mfma_f32_16x16x32_bf16 v[68:71], v[128:131], v[230:233], v[68:71]
	v_mfma_f32_16x16x32_bf16 v[64:67], v[136:139], v[230:233], v[64:67]
	v_mfma_f32_16x16x32_bf16 v[116:119], v[132:135], v[196:199], v[116:119]
	v_mfma_f32_16x16x32_bf16 v[112:115], v[140:143], v[196:199], v[112:115]
	v_mfma_f32_16x16x32_bf16 v[100:103], v[132:135], v[218:221], v[100:103]
	v_mfma_f32_16x16x32_bf16 v[96:99], v[140:143], v[218:221], v[96:99]
	v_mfma_f32_16x16x32_bf16 v[84:87], v[132:135], v[226:229], v[84:87]
	v_mfma_f32_16x16x32_bf16 v[80:83], v[140:143], v[226:229], v[80:83]
	v_mfma_f32_16x16x32_bf16 v[68:71], v[132:135], v[234:237], v[68:71]
	v_mfma_f32_16x16x32_bf16 v[64:67], v[140:143], v[234:237], v[64:67]
	s_setprio 0
	s_setprio 1
	v_mfma_f32_16x16x32_bf16 v[124:127], v[144:147], v[188:191], v[124:127]
	v_mfma_f32_16x16x32_bf16 v[120:123], v[180:183], v[188:191], v[120:123]
	v_mfma_f32_16x16x32_bf16 v[108:111], v[144:147], v[200:203], v[108:111]
	v_mfma_f32_16x16x32_bf16 v[104:107], v[180:183], v[200:203], v[104:107]
	v_mfma_f32_16x16x32_bf16 v[92:95], v[144:147], v[222:225], v[92:95]
	v_mfma_f32_16x16x32_bf16 v[88:91], v[180:183], v[222:225], v[88:91]
	v_mfma_f32_16x16x32_bf16 v[76:79], v[144:147], v[230:233], v[76:79]
	v_mfma_f32_16x16x32_bf16 v[72:75], v[180:183], v[230:233], v[72:75]
	v_mfma_f32_16x16x32_bf16 v[124:127], v[148:151], v[196:199], v[124:127]
	v_mfma_f32_16x16x32_bf16 v[120:123], v[184:187], v[196:199], v[120:123]
	v_mfma_f32_16x16x32_bf16 v[108:111], v[148:151], v[218:221], v[108:111]
	v_mfma_f32_16x16x32_bf16 v[104:107], v[184:187], v[218:221], v[104:107]
	v_mfma_f32_16x16x32_bf16 v[92:95], v[148:151], v[226:229], v[92:95]
	v_mfma_f32_16x16x32_bf16 v[88:91], v[184:187], v[226:229], v[88:91]
	v_mfma_f32_16x16x32_bf16 v[76:79], v[148:151], v[234:237], v[76:79]
	v_mfma_f32_16x16x32_bf16 v[72:75], v[184:187], v[234:237], v[72:75]
	s_setprio 0
	s_barrier
	s_add_i32 s14, vcc_hi, s73
	v_lshl_add_u64 v[204:205], s[46:47], 0, v[164:165]
	s_mov_b32 m0, s14
	ds_read_b128 v[188:191], v194 offset:16384
	ds_read_b128 v[196:199], v194 offset:17408
	ds_read_b128 v[200:203], v194 offset:18432
	ds_read_b128 v[218:221], v194 offset:19456
	ds_read_b128 v[222:225], v194 offset:20480
	ds_read_b128 v[226:229], v194 offset:21504
	ds_read_b128 v[230:233], v194 offset:22528
	ds_read_b128 v[234:237], v194 offset:23552
	global_load_lds_dwordx4 v[204:205], off
	s_add_i32 m0, s14, 0x2000
	s_add_u32 s14, s46, 0x40000
	v_lshl_add_u64 v[238:239], s[46:47], 0, v[168:169]
	s_addc_u32 s15, s47, 0
	s_add_i32 s16, s16, s73
	global_load_lds_dwordx4 v[238:239], off
	s_waitcnt vmcnt(4)
	s_waitcnt lgkmcnt(0)
	s_barrier
; #define PG8_STAGE(bufoff, gbase, voff) do { _Pragma("unroll") for (int _i = 0; _i < 2; ++_i) \
;         __builtin_amdgcn_global_load_lds((const unsigned*)((const char*)(gbase) + (voff)[_i]), (LAS unsigned*)(lds + (bufoff) + ldsw + _i * 8192), 16, 0, 0); } while (0)
; #define PG8_LDA(dst, b, h) do { _Pragma("unroll") for (int m = 0; m < 4; ++m) _Pragma("unroll") for (int k = 0; k < 2; ++k) dst[m][k] = *(const LAS bf16x8*)(lds + PG8_SA(b, h) + aoff + m * 2048 + k * 1024); } while (0)
; #define PG8_LDB(dst, b, h) do { _Pragma("unroll") for (int n = 0; n < 2; ++n) _Pragma("unroll") for (int k = 0; k < 2; ++k) dst[n][k] = *(const LAS bf16x8*)(lds + PG8_SB(b, h) + boff + n * 2048 + k * 1024); } while (0)
; #define PG8_MMA(ai, bj, At, Bt) do { __builtin_amdgcn_s_setprio(1); _Pragma("unroll") for (int m = 0; m < 4; ++m) _Pragma("unroll") for (int n = 0; n < 2; ++n) _Pragma("unroll") for (int k = 0; k < 2; ++k) \
;         acc[ai][bj][m][n] = __builtin_amdgcn_mfma_f32_16x16x32_bf16(Bt[n][k], At[m][k], acc[ai][bj][m][n], 0, 0, 0); __builtin_amdgcn_s_setprio(0); } while (0)
; #define PG8_WAIT_V(n) asm volatile("s_waitcnt vmcnt(" #n ")" ::: "memory")
; #define PG8_WAIT_L(n) asm volatile("s_waitcnt lgkmcnt(" #n ")" ::: "memory")
; #define PG8_BAR __builtin_amdgcn_s_barrier()
; #define PG8_SCHED __builtin_amdgcn_sched_barrier(0)
; template <class Epi, class Sched, bool ALIGN_EPI = false, bool SP2 = false>
; __device__ __forceinline__ void gemm_phase(LAS unsigned char* lds, const Gemm g, const Sched& S, const Epi& E) {
;     ...
;             PG8_WAIT_V(8); PG8_WAIT_L(0); PG8_BAR; PG8_MMA(1, 0, At, B0); PG8_MMA(1, 1, At, B1); PG8_BAR; PG8_SCHED;
;             PG8_LDB(B0, 1, 0); PG8_LDB(B1, 1, 1); PG8_SCHED; PG8_LDA(At, 1, 0); PG8_STAGE(PG8_SA(0, 1), a2 + hstep, voffA);
;             PG8_WAIT_V(8); PG8_WAIT_L(0); PG8_BAR; PG8_MMA(0, 0, At, B0); PG8_MMA(0, 1, At, B1); PG8_BAR; PG8_SCHED;
;             PG8_LDA(At, 1, 1); PG8_STAGE(PG8_SB(1, 0), b3, voffB); PG8_STAGE(PG8_SB(1, 1), b3 + hstep, voffB); PG8_STAGE(PG8_SA(1, 0), a3, voffA);
	s_setprio 1
	s_waitcnt lgkmcnt(0)
	v_mfma_f32_16x16x32_bf16 v[52:55], v[128:131], v[188:191], v[52:55]
	v_mfma_f32_16x16x32_bf16 v[48:51], v[136:139], v[188:191], v[48:51]
	v_mfma_f32_16x16x32_bf16 v[36:39], v[128:131], v[200:203], v[36:39]
	v_lshl_add_u64 v[240:241], s[14:15], 0, v[164:165]
	s_mov_b32 m0, s16
	v_lshl_add_u64 v[242:243], s[96:97], 0, v[166:167]
	v_mfma_f32_16x16x32_bf16 v[32:35], v[136:139], v[200:203], v[32:35]
	global_load_lds_dwordx4 v[240:241], off
	v_mfma_f32_16x16x32_bf16 v[20:23], v[128:131], v[222:225], v[20:23]
	v_mfma_f32_16x16x32_bf16 v[16:19], v[136:139], v[222:225], v[16:19]
	v_mfma_f32_16x16x32_bf16 v[4:7], v[128:131], v[230:233], v[4:7]
	v_mfma_f32_16x16x32_bf16 v[0:3], v[136:139], v[230:233], v[0:3]
	v_mfma_f32_16x16x32_bf16 v[52:55], v[132:135], v[196:199], v[52:55]
	v_mfma_f32_16x16x32_bf16 v[48:51], v[140:143], v[196:199], v[48:51]
	v_lshl_add_u64 v[240:241], s[14:15], 0, v[168:169]
	s_add_i32 m0, s16, 0x2000
	v_mfma_f32_16x16x32_bf16 v[36:39], v[132:135], v[218:221], v[36:39]
	global_load_lds_dwordx4 v[240:241], off
	v_mfma_f32_16x16x32_bf16 v[32:35], v[140:143], v[218:221], v[32:35]
	v_mfma_f32_16x16x32_bf16 v[20:23], v[132:135], v[226:229], v[20:23]
	v_mfma_f32_16x16x32_bf16 v[16:19], v[140:143], v[226:229], v[16:19]
	v_mfma_f32_16x16x32_bf16 v[4:7], v[132:135], v[234:237], v[4:7]
	v_mfma_f32_16x16x32_bf16 v[0:3], v[140:143], v[234:237], v[0:3]
	s_setprio 0
	s_setprio 1
	v_mfma_f32_16x16x32_bf16 v[60:63], v[144:147], v[188:191], v[60:63]
	v_mfma_f32_16x16x32_bf16 v[56:59], v[180:183], v[188:191], v[56:59]
	v_lshl_add_u64 v[240:241], s[96:97], 0, v[162:163]
	s_mov_b32 m0, s93
	v_mfma_f32_16x16x32_bf16 v[44:47], v[144:147], v[200:203], v[44:47]
	global_load_lds_dwordx4 v[240:241], off
	v_mfma_f32_16x16x32_bf16 v[40:43], v[180:183], v[200:203], v[40:43]
	v_mfma_f32_16x16x32_bf16 v[28:31], v[144:147], v[222:225], v[28:31]
	v_mfma_f32_16x16x32_bf16 v[24:27], v[180:183], v[222:225], v[24:27]
	v_mfma_f32_16x16x32_bf16 v[12:15], v[144:147], v[230:233], v[12:15]
	v_mfma_f32_16x16x32_bf16 v[8:11], v[180:183], v[230:233], v[8:11]
	v_mfma_f32_16x16x32_bf16 v[60:63], v[148:151], v[196:199], v[60:63]
	v_mfma_f32_16x16x32_bf16 v[56:59], v[184:187], v[196:199], v[56:59]
	s_mov_b32 m0, s4
	v_mfma_f32_16x16x32_bf16 v[44:47], v[148:151], v[218:221], v[44:47]
	global_load_lds_dwordx4 v[242:243], off
	v_mfma_f32_16x16x32_bf16 v[40:43], v[184:187], v[218:221], v[40:43]
	v_mfma_f32_16x16x32_bf16 v[28:31], v[148:151], v[226:229], v[28:31]
	v_mfma_f32_16x16x32_bf16 v[24:27], v[184:187], v[226:229], v[24:27]
	v_mfma_f32_16x16x32_bf16 v[12:15], v[148:151], v[234:237], v[12:15]
	v_mfma_f32_16x16x32_bf16 v[8:11], v[184:187], v[234:237], v[8:11]
	s_setprio 0
	s_barrier
	s_add_i32 s16, 0, 0x18000
	s_add_i32 s17, 0, 0x1c000
	v_add_u32_e32 v140, s16, v192
	v_add_u32_e32 v152, s17, v192
	ds_read_b128 v[128:131], v140
	ds_read_b128 v[132:135], v140 offset:1024
	ds_read_b128 v[136:139], v140 offset:2048
	ds_read_b128 v[140:143], v140 offset:3072
	ds_read_b128 v[144:147], v152
	ds_read_b128 v[148:151], v152 offset:1024
	ds_read_b128 v[180:183], v152 offset:2048
	ds_read_b128 v[184:187], v152 offset:3072
	s_add_u32 s14, s96, 0x40000
	s_addc_u32 s15, s97, 0
	s_mov_b32 m0, s5
	v_lshl_add_u64 v[244:245], s[14:15], 0, v[162:163]
	ds_read_b128 v[188:191], v194 offset:32768
	ds_read_b128 v[196:199], v194 offset:33792
	ds_read_b128 v[200:203], v194 offset:34816
	ds_read_b128 v[218:221], v194 offset:35840
	ds_read_b128 v[222:225], v194 offset:36864
	ds_read_b128 v[226:229], v194 offset:37888
	ds_read_b128 v[230:233], v194 offset:38912
	ds_read_b128 v[234:237], v194 offset:39936
	global_load_lds_dwordx4 v[244:245], off
	v_lshl_add_u64 v[244:245], s[14:15], 0, v[166:167]
	s_mov_b32 m0, s6
	s_nop 0
	global_load_lds_dwordx4 v[244:245], off
	s_waitcnt vmcnt(8)
	s_waitcnt lgkmcnt(0)
	s_barrier
; #define PG8_STAGE(bufoff, gbase, voff) do { _Pragma("unroll") for (int _i = 0; _i < 2; ++_i) \
;         __builtin_amdgcn_global_load_lds((const unsigned*)((const char*)(gbase) + (voff)[_i]), (LAS unsigned*)(lds + (bufoff) + ldsw + _i * 8192), 16, 0, 0); } while (0)
; #define PG8_LDA(dst, b, h) do { _Pragma("unroll") for (int m = 0; m < 4; ++m) _Pragma("unroll") for (int k = 0; k < 2; ++k) dst[m][k] = *(const LAS bf16x8*)(lds + PG8_SA(b, h) + aoff + m * 2048 + k * 1024); } while (0)
; #define PG8_MMA(ai, bj, At, Bt) do { __builtin_amdgcn_s_setprio(1); _Pragma("unroll") for (int m = 0; m < 4; ++m) _Pragma("unroll") for (int n = 0; n < 2; ++n) _Pragma("unroll") for (int k = 0; k < 2; ++k) \
;         acc[ai][bj][m][n] = __builtin_amdgcn_mfma_f32_16x16x32_bf16(Bt[n][k], At[m][k], acc[ai][bj][m][n], 0, 0, 0); __builtin_amdgcn_s_setprio(0); } while (0)
; #define PG8_WAIT_V(n) asm volatile("s_waitcnt vmcnt(" #n ")" ::: "memory")
; #define PG8_WAIT_L(n) asm volatile("s_waitcnt lgkmcnt(" #n ")" ::: "memory")
; #define PG8_BAR __builtin_amdgcn_s_barrier()
; #define PG8_SCHED __builtin_amdgcn_sched_barrier(0)
; template <class Epi, class Sched, bool ALIGN_EPI = false, bool SP2 = false>
; __device__ __forceinline__ void gemm_phase(LAS unsigned char* lds, const Gemm g, const Sched& S, const Epi& E) {
;     ...
;         for (int t = 0; t < nt; t += 2) {
;     ...
;             PG8_WAIT_V(8); PG8_WAIT_L(0); PG8_BAR; PG8_MMA(0, 0, At, B0); PG8_MMA(0, 1, At, B1); PG8_BAR; PG8_SCHED;
;             PG8_LDA(At, 1, 1); PG8_STAGE(PG8_SB(1, 0), b3, voffB); PG8_STAGE(PG8_SB(1, 1), b3 + hstep, voffB); PG8_STAGE(PG8_SA(1, 0), a3, voffA);
;             PG8_WAIT_V(8); PG8_WAIT_L(0); PG8_BAR; PG8_MMA(1, 0, At, B0); PG8_MMA(1, 1, At, B1); PG8_BAR; PG8_SCHED;
	s_setprio 1
	s_waitcnt lgkmcnt(0)
	v_mfma_f32_16x16x32_bf16 v[116:119], v[128:131], v[188:191], v[116:119]
	v_mfma_f32_16x16x32_bf16 v[112:115], v[136:139], v[188:191], v[112:115]
	v_mfma_f32_16x16x32_bf16 v[100:103], v[128:131], v[200:203], v[100:103]
	v_mfma_f32_16x16x32_bf16 v[96:99], v[136:139], v[200:203], v[96:99]
	v_mfma_f32_16x16x32_bf16 v[84:87], v[128:131], v[222:225], v[84:87]
	v_mfma_f32_16x16x32_bf16 v[80:83], v[136:139], v[222:225], v[80:83]
	v_mfma_f32_16x16x32_bf16 v[68:71], v[128:131], v[230:233], v[68:71]
	v_mfma_f32_16x16x32_bf16 v[64:67], v[136:139], v[230:233], v[64:67]
	v_mfma_f32_16x16x32_bf16 v[116:119], v[132:135], v[196:199], v[116:119]
	v_mfma_f32_16x16x32_bf16 v[112:115], v[140:143], v[196:199], v[112:115]
	v_mfma_f32_16x16x32_bf16 v[100:103], v[132:135], v[218:221], v[100:103]
	v_mfma_f32_16x16x32_bf16 v[96:99], v[140:143], v[218:221], v[96:99]
	v_mfma_f32_16x16x32_bf16 v[84:87], v[132:135], v[226:229], v[84:87]
	v_mfma_f32_16x16x32_bf16 v[80:83], v[140:143], v[226:229], v[80:83]
	v_mfma_f32_16x16x32_bf16 v[68:71], v[132:135], v[234:237], v[68:71]
	v_mfma_f32_16x16x32_bf16 v[64:67], v[140:143], v[234:237], v[64:67]
	s_setprio 0
	s_setprio 1
	v_mfma_f32_16x16x32_bf16 v[124:127], v[144:147], v[188:191], v[124:127]
	v_mfma_f32_16x16x32_bf16 v[120:123], v[180:183], v[188:191], v[120:123]
	v_mfma_f32_16x16x32_bf16 v[108:111], v[144:147], v[200:203], v[108:111]
	v_mfma_f32_16x16x32_bf16 v[104:107], v[180:183], v[200:203], v[104:107]
	v_mfma_f32_16x16x32_bf16 v[92:95], v[144:147], v[222:225], v[92:95]
	v_mfma_f32_16x16x32_bf16 v[88:91], v[180:183], v[222:225], v[88:91]
	v_mfma_f32_16x16x32_bf16 v[76:79], v[144:147], v[230:233], v[76:79]
	v_mfma_f32_16x16x32_bf16 v[72:75], v[180:183], v[230:233], v[72:75]
	v_mfma_f32_16x16x32_bf16 v[124:127], v[148:151], v[196:199], v[124:127]
	v_mfma_f32_16x16x32_bf16 v[120:123], v[184:187], v[196:199], v[120:123]
	v_mfma_f32_16x16x32_bf16 v[108:111], v[148:151], v[218:221], v[108:111]
	v_mfma_f32_16x16x32_bf16 v[104:107], v[184:187], v[218:221], v[104:107]
	v_mfma_f32_16x16x32_bf16 v[92:95], v[148:151], v[226:229], v[92:95]
	v_mfma_f32_16x16x32_bf16 v[88:91], v[184:187], v[226:229], v[88:91]
	v_mfma_f32_16x16x32_bf16 v[76:79], v[148:151], v[234:237], v[76:79]
	v_mfma_f32_16x16x32_bf16 v[72:75], v[184:187], v[234:237], v[72:75]
	s_setprio 0
	s_barrier
	s_add_i32 s14, s16, s73
	v_lshl_add_u64 v[204:205], v[204:205], 0, s[30:31]
	s_mov_b32 m0, s14
	ds_read_b128 v[188:191], v194 offset:49152
	ds_read_b128 v[196:199], v194 offset:50176
	ds_read_b128 v[200:203], v194 offset:51200
	ds_read_b128 v[218:221], v194 offset:52224
	ds_read_b128 v[222:225], v194 offset:53248
	ds_read_b128 v[226:229], v194 offset:54272
	ds_read_b128 v[230:233], v194 offset:55296
	ds_read_b128 v[234:237], v194 offset:56320
	global_load_lds_dwordx4 v[204:205], off
	s_add_i32 m0, s14, 0x2000
	s_add_u32 s14, s46, 0x40080
	v_lshl_add_u64 v[204:205], v[238:239], 0, s[30:31]
	s_addc_u32 s15, s47, 0
	s_add_i32 s16, s17, s73
	global_load_lds_dwordx4 v[204:205], off
	s_waitcnt vmcnt(4)
	s_waitcnt lgkmcnt(0)
	s_barrier
	s_setprio 1
	s_waitcnt lgkmcnt(0)
	v_mfma_f32_16x16x32_bf16 v[52:55], v[128:131], v[188:191], v[52:55]
	v_mfma_f32_16x16x32_bf16 v[48:51], v[136:139], v[188:191], v[48:51]
	v_mfma_f32_16x16x32_bf16 v[36:39], v[128:131], v[200:203], v[36:39]
	v_lshl_add_u64 v[204:205], s[14:15], 0, v[164:165]
	s_mov_b32 m0, s16
	v_mfma_f32_16x16x32_bf16 v[32:35], v[136:139], v[200:203], v[32:35]
	global_load_lds_dwordx4 v[204:205], off
	v_mfma_f32_16x16x32_bf16 v[20:23], v[128:131], v[222:225], v[20:23]
	v_mfma_f32_16x16x32_bf16 v[16:19], v[136:139], v[222:225], v[16:19]
	v_mfma_f32_16x16x32_bf16 v[4:7], v[128:131], v[230:233], v[4:7]
	v_mfma_f32_16x16x32_bf16 v[0:3], v[136:139], v[230:233], v[0:3]
	v_mfma_f32_16x16x32_bf16 v[52:55], v[132:135], v[196:199], v[52:55]
	v_mfma_f32_16x16x32_bf16 v[48:51], v[140:143], v[196:199], v[48:51]
	v_lshl_add_u64 v[204:205], s[14:15], 0, v[168:169]
	s_add_i32 m0, s16, 0x2000
	v_mfma_f32_16x16x32_bf16 v[36:39], v[132:135], v[218:221], v[36:39]
	global_load_lds_dwordx4 v[204:205], off
	v_mfma_f32_16x16x32_bf16 v[32:35], v[140:143], v[218:221], v[32:35]
	v_mfma_f32_16x16x32_bf16 v[20:23], v[132:135], v[226:229], v[20:23]
	v_mfma_f32_16x16x32_bf16 v[16:19], v[140:143], v[226:229], v[16:19]
	v_mfma_f32_16x16x32_bf16 v[4:7], v[132:135], v[234:237], v[4:7]
	v_mfma_f32_16x16x32_bf16 v[0:3], v[140:143], v[234:237], v[0:3]
	s_setprio 0
	s_setprio 1
	v_mfma_f32_16x16x32_bf16 v[60:63], v[144:147], v[188:191], v[60:63]
	v_mfma_f32_16x16x32_bf16 v[56:59], v[180:183], v[188:191], v[56:59]
	v_lshl_add_u64 v[204:205], v[240:241], 0, s[30:31]
	s_mov_b32 m0, s8
	v_mfma_f32_16x16x32_bf16 v[44:47], v[144:147], v[200:203], v[44:47]
	global_load_lds_dwordx4 v[204:205], off
	v_mfma_f32_16x16x32_bf16 v[40:43], v[180:183], v[200:203], v[40:43]
	v_mfma_f32_16x16x32_bf16 v[28:31], v[144:147], v[222:225], v[28:31]
	v_mfma_f32_16x16x32_bf16 v[24:27], v[180:183], v[222:225], v[24:27]
	v_mfma_f32_16x16x32_bf16 v[12:15], v[144:147], v[230:233], v[12:15]
	v_mfma_f32_16x16x32_bf16 v[8:11], v[180:183], v[230:233], v[8:11]
	v_mfma_f32_16x16x32_bf16 v[60:63], v[148:151], v[196:199], v[60:63]
	v_mfma_f32_16x16x32_bf16 v[56:59], v[184:187], v[196:199], v[56:59]
	v_lshl_add_u64 v[204:205], v[242:243], 0, s[30:31]
	s_mov_b32 m0, s9
	v_mfma_f32_16x16x32_bf16 v[44:47], v[148:151], v[218:221], v[44:47]
	global_load_lds_dwordx4 v[204:205], off
	v_mfma_f32_16x16x32_bf16 v[40:43], v[184:187], v[218:221], v[40:43]
	v_mfma_f32_16x16x32_bf16 v[28:31], v[148:151], v[226:229], v[28:31]
	v_mfma_f32_16x16x32_bf16 v[24:27], v[184:187], v[226:229], v[24:27]
	v_mfma_f32_16x16x32_bf16 v[12:15], v[148:151], v[234:237], v[12:15]
	v_mfma_f32_16x16x32_bf16 v[8:11], v[184:187], v[234:237], v[8:11]
	s_setprio 0
	s_barrier
	s_add_i32 vcc_lo, vcc_lo, 2
	s_add_u32 s42, s42, 0x100
	s_addc_u32 s43, s43, 0
	s_add_u32 s98, s98, 0x100
	s_addc_u32 s99, s99, 0
	s_cmp_gt_u32 vcc_lo, 13
	s_cbranch_scc0 .LBB0_122
	s_and_b64 vcc, exec, s[38:39]
	s_cbranch_vccz .LBB0_125
	s_barrier

; #define PG8_STAGE(bufoff, gbase, voff) do { _Pragma("unroll") for (int _i = 0; _i < 2; ++_i) \
;         __builtin_amdgcn_global_load_lds((const unsigned*)((const char*)(gbase) + (voff)[_i]), (LAS unsigned*)(lds + (bufoff) + ldsw + _i * 8192), 16, 0, 0); } while (0)
; #define PG8_LDA(dst, b, h) do { _Pragma("unroll") for (int m = 0; m < 4; ++m) _Pragma("unroll") for (int k = 0; k < 2; ++k) dst[m][k] = *(const LAS bf16x8*)(lds + PG8_SA(b, h) + aoff + m * 2048 + k * 1024); } while (0)
; #define PG8_LDB(dst, b, h) do { _Pragma("unroll") for (int n = 0; n < 2; ++n) _Pragma("unroll") for (int k = 0; k < 2; ++k) dst[n][k] = *(const LAS bf16x8*)(lds + PG8_SB(b, h) + boff + n * 2048 + k * 1024); } while (0)
; #define PG8_MMA(ai, bj, At, Bt) do { __builtin_amdgcn_s_setprio(1); _Pragma("unroll") for (int m = 0; m < 4; ++m) _Pragma("unroll") for (int n = 0; n < 2; ++n) _Pragma("unroll") for (int k = 0; k < 2; ++k) \
;         acc[ai][bj][m][n] = __builtin_amdgcn_mfma_f32_16x16x32_bf16(Bt[n][k], At[m][k], acc[ai][bj][m][n], 0, 0, 0); __builtin_amdgcn_s_setprio(0); } while (0)
; #define PG8_WAIT_V(n) asm volatile("s_waitcnt vmcnt(" #n ")" ::: "memory")
; #define PG8_WAIT_L(n) asm volatile("s_waitcnt lgkmcnt(" #n ")" ::: "memory")
; #define PG8_BAR __builtin_amdgcn_s_barrier()
; #define PG8_SCHED __builtin_amdgcn_sched_barrier(0)
; template <class Epi, class Sched, bool ALIGN_EPI = false, bool SP2 = false>
; __device__ __forceinline__ void gemm_phase(LAS unsigned char* lds, const Gemm g, const Sched& S, const Epi& E) {
;     ...
;             PG8_LDB(B0, 0, 0); PG8_LDB(B1, 0, 1); PG8_SCHED; PG8_LDA(At, 0, 0); PG8_STAGE(PG8_SA(1, 1), a1 + hstep, voffA);
;             PG8_WAIT_V(8); PG8_WAIT_L(0); PG8_BAR; PG8_MMA(0, 0, At, B0); PG8_MMA(0, 1, At, B1); PG8_BAR; PG8_SCHED;
;             PG8_LDA(At, 0, 1); PG8_STAGE(PG8_SB(0, 0), b2, voffB); PG8_STAGE(PG8_SB(0, 1), b2 + hstep, voffB); PG8_STAGE(PG8_SA(0, 0), a2, voffA);
;             PG8_WAIT_V(8); PG8_WAIT_L(0); PG8_BAR; PG8_MMA(1, 0, At, B0); PG8_MMA(1, 1, At, B1); PG8_BAR; PG8_SCHED;
.LBB0_418:
	s_add_u32 s13, s24, 0xfffc0080
	s_addc_u32 s14, s25, -1
	s_add_i32 s15, 0, 0x10000
	s_cmp_eq_u32 s12, 12
	s_cselect_b32 s39, s6, s14
	s_cselect_b32 s38, s7, s13
	s_cselect_b32 s37, s8, s11
	s_cselect_b32 s36, s9, s10
	s_add_i32 s13, 0, 0x14000
	v_add_u32_e32 v140, s15, v218
	v_add_u32_e32 v152, s13, v218
	ds_read_b128 v[128:131], v140
	ds_read_b128 v[132:135], v140 offset:1024
	ds_read_b128 v[136:139], v140 offset:2048
	ds_read_b128 v[140:143], v140 offset:3072
	ds_read_b128 v[166:169], v152
	ds_read_b128 v[170:173], v152 offset:1024
	ds_read_b128 v[174:177], v152 offset:2048
	ds_read_b128 v[178:181], v152 offset:3072
	v_lshl_add_u64 v[230:231], s[24:25], 0, v[162:163]
	s_add_i32 m0, s71, 0xc000
	ds_read_b128 v[182:185], v221
	ds_read_b128 v[186:189], v221 offset:1024
	ds_read_b128 v[190:193], v221 offset:2048
	ds_read_b128 v[194:197], v221 offset:3072
	ds_read_b128 v[198:201], v221 offset:4096
	ds_read_b128 v[202:205], v221 offset:5120
	ds_read_b128 v[222:225], v221 offset:6144
	ds_read_b128 v[226:229], v221 offset:7168
	global_load_lds_dwordx4 v[230:231], off
	v_lshl_add_u64 v[230:231], s[24:25], 0, v[164:165]
	s_add_i32 m0, s71, 0xe000
	s_nop 0
	global_load_lds_dwordx4 v[230:231], off
	s_waitcnt vmcnt(8)
	s_waitcnt lgkmcnt(0)
	s_barrier
	s_setprio 1
	s_waitcnt lgkmcnt(0)
	v_mfma_f32_16x16x32_bf16 v[124:127], v[128:131], v[182:185], v[124:127]
	v_mfma_f32_16x16x32_bf16 v[120:123], v[136:139], v[182:185], v[120:123]
	v_mfma_f32_16x16x32_bf16 v[108:111], v[128:131], v[190:193], v[108:111]
	v_mfma_f32_16x16x32_bf16 v[104:107], v[136:139], v[190:193], v[104:107]
	v_mfma_f32_16x16x32_bf16 v[92:95], v[128:131], v[198:201], v[92:95]
	v_mfma_f32_16x16x32_bf16 v[88:91], v[136:139], v[198:201], v[88:91]
	v_mfma_f32_16x16x32_bf16 v[76:79], v[128:131], v[222:225], v[76:79]
	v_mfma_f32_16x16x32_bf16 v[72:75], v[136:139], v[222:225], v[72:75]
	v_mfma_f32_16x16x32_bf16 v[124:127], v[132:135], v[186:189], v[124:127]
	v_mfma_f32_16x16x32_bf16 v[120:123], v[140:143], v[186:189], v[120:123]
	v_mfma_f32_16x16x32_bf16 v[108:111], v[132:135], v[194:197], v[108:111]
	v_mfma_f32_16x16x32_bf16 v[104:107], v[140:143], v[194:197], v[104:107]
	v_mfma_f32_16x16x32_bf16 v[92:95], v[132:135], v[202:205], v[92:95]
	v_mfma_f32_16x16x32_bf16 v[88:91], v[140:143], v[202:205], v[88:91]
	v_mfma_f32_16x16x32_bf16 v[76:79], v[132:135], v[226:229], v[76:79]
	v_mfma_f32_16x16x32_bf16 v[72:75], v[140:143], v[226:229], v[72:75]
	s_setprio 0
	s_setprio 1
	v_mfma_f32_16x16x32_bf16 v[116:119], v[166:169], v[182:185], v[116:119]
	v_mfma_f32_16x16x32_bf16 v[112:115], v[174:177], v[182:185], v[112:115]
	v_mfma_f32_16x16x32_bf16 v[100:103], v[166:169], v[190:193], v[100:103]
	v_mfma_f32_16x16x32_bf16 v[96:99], v[174:177], v[190:193], v[96:99]
	v_mfma_f32_16x16x32_bf16 v[84:87], v[166:169], v[198:201], v[84:87]
	v_mfma_f32_16x16x32_bf16 v[80:83], v[174:177], v[198:201], v[80:83]
	v_mfma_f32_16x16x32_bf16 v[68:71], v[166:169], v[222:225], v[68:71]
	v_mfma_f32_16x16x32_bf16 v[64:67], v[174:177], v[222:225], v[64:67]
	v_mfma_f32_16x16x32_bf16 v[116:119], v[170:173], v[186:189], v[116:119]
	v_mfma_f32_16x16x32_bf16 v[112:115], v[178:181], v[186:189], v[112:115]
	v_mfma_f32_16x16x32_bf16 v[100:103], v[170:173], v[194:197], v[100:103]
	v_mfma_f32_16x16x32_bf16 v[96:99], v[178:181], v[194:197], v[96:99]
	v_mfma_f32_16x16x32_bf16 v[84:87], v[170:173], v[202:205], v[84:87]
	v_mfma_f32_16x16x32_bf16 v[80:83], v[178:181], v[202:205], v[80:83]
	v_mfma_f32_16x16x32_bf16 v[68:71], v[170:173], v[226:229], v[68:71]
	v_mfma_f32_16x16x32_bf16 v[64:67], v[178:181], v[226:229], v[64:67]
	s_setprio 0
	s_barrier
	s_add_i32 s14, s15, s70
	v_lshl_add_u64 v[230:231], s[36:37], 0, v[148:149]
	s_mov_b32 m0, s14
	ds_read_b128 v[182:185], v221 offset:16384
	ds_read_b128 v[186:189], v221 offset:17408
	ds_read_b128 v[190:193], v221 offset:18432
	ds_read_b128 v[194:197], v221 offset:19456
	ds_read_b128 v[198:201], v221 offset:20480
	ds_read_b128 v[202:205], v221 offset:21504
	ds_read_b128 v[222:225], v221 offset:22528
	ds_read_b128 v[226:229], v221 offset:23552
	global_load_lds_dwordx4 v[230:231], off
	s_add_i32 m0, s14, 0x2000
	s_add_u32 s14, s36, 0x40000
	v_lshl_add_u64 v[232:233], s[36:37], 0, v[144:145]
	s_addc_u32 s15, s37, 0
	s_add_i32 s13, s13, s70
	global_load_lds_dwordx4 v[232:233], off
	s_waitcnt vmcnt(4)
	s_waitcnt lgkmcnt(0)
	s_barrier
; #define PG8_STAGE(bufoff, gbase, voff) do { _Pragma("unroll") for (int _i = 0; _i < 2; ++_i) \
;         __builtin_amdgcn_global_load_lds((const unsigned*)((const char*)(gbase) + (voff)[_i]), (LAS unsigned*)(lds + (bufoff) + ldsw + _i * 8192), 16, 0, 0); } while (0)
; #define PG8_LDA(dst, b, h) do { _Pragma("unroll") for (int m = 0; m < 4; ++m) _Pragma("unroll") for (int k = 0; k < 2; ++k) dst[m][k] = *(const LAS bf16x8*)(lds + PG8_SA(b, h) + aoff + m * 2048 + k * 1024); } while (0)
; #define PG8_LDB(dst, b, h) do { _Pragma("unroll") for (int n = 0; n < 2; ++n) _Pragma("unroll") for (int k = 0; k < 2; ++k) dst[n][k] = *(const LAS bf16x8*)(lds + PG8_SB(b, h) + boff + n * 2048 + k * 1024); } while (0)
; #define PG8_MMA(ai, bj, At, Bt) do { __builtin_amdgcn_s_setprio(1); _Pragma("unroll") for (int m = 0; m < 4; ++m) _Pragma("unroll") for (int n = 0; n < 2; ++n) _Pragma("unroll") for (int k = 0; k < 2; ++k) \
;         acc[ai][bj][m][n] = __builtin_amdgcn_mfma_f32_16x16x32_bf16(Bt[n][k], At[m][k], acc[ai][bj][m][n], 0, 0, 0); __builtin_amdgcn_s_setprio(0); } while (0)
; #define PG8_WAIT_V(n) asm volatile("s_waitcnt vmcnt(" #n ")" ::: "memory")
; #define PG8_WAIT_L(n) asm volatile("s_waitcnt lgkmcnt(" #n ")" ::: "memory")
; #define PG8_BAR __builtin_amdgcn_s_barrier()
; #define PG8_SCHED __builtin_amdgcn_sched_barrier(0)
; template <class Epi, class Sched, bool ALIGN_EPI = false, bool SP2 = false>
; __device__ __forceinline__ void gemm_phase(LAS unsigned char* lds, const Gemm g, const Sched& S, const Epi& E) {
;     ...
;             PG8_WAIT_V(8); PG8_WAIT_L(0); PG8_BAR; PG8_MMA(1, 0, At, B0); PG8_MMA(1, 1, At, B1); PG8_BAR; PG8_SCHED;
;             PG8_LDB(B0, 1, 0); PG8_LDB(B1, 1, 1); PG8_SCHED; PG8_LDA(At, 1, 0); PG8_STAGE(PG8_SA(0, 1), a2 + hstep, voffA);
;             PG8_WAIT_V(8); PG8_WAIT_L(0); PG8_BAR; PG8_MMA(0, 0, At, B0); PG8_MMA(0, 1, At, B1); PG8_BAR; PG8_SCHED;
;             PG8_LDA(At, 1, 1); PG8_STAGE(PG8_SB(1, 0), b3, voffB); PG8_STAGE(PG8_SB(1, 1), b3 + hstep, voffB); PG8_STAGE(PG8_SA(1, 0), a3, voffA);
	s_setprio 1
	s_waitcnt lgkmcnt(0)
	v_mfma_f32_16x16x32_bf16 v[60:63], v[128:131], v[182:185], v[60:63]
	v_mfma_f32_16x16x32_bf16 v[56:59], v[136:139], v[182:185], v[56:59]
	v_mfma_f32_16x16x32_bf16 v[44:47], v[128:131], v[190:193], v[44:47]
	v_lshl_add_u64 v[234:235], s[14:15], 0, v[148:149]
	s_mov_b32 m0, s13
	v_lshl_add_u64 v[236:237], s[38:39], 0, v[146:147]
	v_mfma_f32_16x16x32_bf16 v[40:43], v[136:139], v[190:193], v[40:43]
	global_load_lds_dwordx4 v[234:235], off
	v_mfma_f32_16x16x32_bf16 v[28:31], v[128:131], v[198:201], v[28:31]
	v_mfma_f32_16x16x32_bf16 v[24:27], v[136:139], v[198:201], v[24:27]
	v_mfma_f32_16x16x32_bf16 v[12:15], v[128:131], v[222:225], v[12:15]
	v_mfma_f32_16x16x32_bf16 v[8:11], v[136:139], v[222:225], v[8:11]
	v_mfma_f32_16x16x32_bf16 v[60:63], v[132:135], v[186:189], v[60:63]
	v_mfma_f32_16x16x32_bf16 v[56:59], v[140:143], v[186:189], v[56:59]
	v_lshl_add_u64 v[234:235], s[14:15], 0, v[144:145]
	s_add_i32 m0, s13, 0x2000
	v_mfma_f32_16x16x32_bf16 v[44:47], v[132:135], v[194:197], v[44:47]
	global_load_lds_dwordx4 v[234:235], off
	v_mfma_f32_16x16x32_bf16 v[40:43], v[140:143], v[194:197], v[40:43]
	v_mfma_f32_16x16x32_bf16 v[28:31], v[132:135], v[202:205], v[28:31]
	v_mfma_f32_16x16x32_bf16 v[24:27], v[140:143], v[202:205], v[24:27]
	v_mfma_f32_16x16x32_bf16 v[12:15], v[132:135], v[226:229], v[12:15]
	v_mfma_f32_16x16x32_bf16 v[8:11], v[140:143], v[226:229], v[8:11]
	s_setprio 0
	s_setprio 1
	v_mfma_f32_16x16x32_bf16 v[52:55], v[166:169], v[182:185], v[52:55]
	v_mfma_f32_16x16x32_bf16 v[48:51], v[174:177], v[182:185], v[48:51]
	v_lshl_add_u64 v[234:235], s[38:39], 0, v[150:151]
	s_mov_b32 m0, s71
	v_mfma_f32_16x16x32_bf16 v[36:39], v[166:169], v[190:193], v[36:39]
	global_load_lds_dwordx4 v[234:235], off
	v_mfma_f32_16x16x32_bf16 v[32:35], v[174:177], v[190:193], v[32:35]
	v_mfma_f32_16x16x32_bf16 v[20:23], v[166:169], v[198:201], v[20:23]
	v_mfma_f32_16x16x32_bf16 v[16:19], v[174:177], v[198:201], v[16:19]
	v_mfma_f32_16x16x32_bf16 v[4:7], v[166:169], v[222:225], v[4:7]
	v_mfma_f32_16x16x32_bf16 v[0:3], v[174:177], v[222:225], v[0:3]
	v_mfma_f32_16x16x32_bf16 v[52:55], v[170:173], v[186:189], v[52:55]
	v_mfma_f32_16x16x32_bf16 v[48:51], v[178:181], v[186:189], v[48:51]
	s_mov_b32 m0, s76
	v_mfma_f32_16x16x32_bf16 v[36:39], v[170:173], v[194:197], v[36:39]
	global_load_lds_dwordx4 v[236:237], off
	v_mfma_f32_16x16x32_bf16 v[32:35], v[178:181], v[194:197], v[32:35]
	v_mfma_f32_16x16x32_bf16 v[20:23], v[170:173], v[202:205], v[20:23]
	v_mfma_f32_16x16x32_bf16 v[16:19], v[178:181], v[202:205], v[16:19]
	v_mfma_f32_16x16x32_bf16 v[4:7], v[170:173], v[226:229], v[4:7]
	v_mfma_f32_16x16x32_bf16 v[0:3], v[178:181], v[226:229], v[0:3]
	s_setprio 0
	s_barrier
	s_add_i32 s13, 0, 0x18000
	s_add_i32 s16, 0, 0x1c000
	v_add_u32_e32 v140, s13, v218
	v_add_u32_e32 v152, s16, v218
	ds_read_b128 v[128:131], v140
	ds_read_b128 v[132:135], v140 offset:1024
	ds_read_b128 v[136:139], v140 offset:2048
	ds_read_b128 v[140:143], v140 offset:3072
	ds_read_b128 v[166:169], v152
	ds_read_b128 v[170:173], v152 offset:1024
	ds_read_b128 v[174:177], v152 offset:2048
	ds_read_b128 v[178:181], v152 offset:3072
	s_add_u32 s14, s38, 0x40000
	s_addc_u32 s15, s39, 0
	s_mov_b32 m0, s92
	v_lshl_add_u64 v[238:239], s[14:15], 0, v[150:151]
	ds_read_b128 v[182:185], v221 offset:32768
	ds_read_b128 v[186:189], v221 offset:33792
	ds_read_b128 v[190:193], v221 offset:34816
	ds_read_b128 v[194:197], v221 offset:35840
	ds_read_b128 v[198:201], v221 offset:36864
	ds_read_b128 v[202:205], v221 offset:37888
	ds_read_b128 v[222:225], v221 offset:38912
	ds_read_b128 v[226:229], v221 offset:39936
	global_load_lds_dwordx4 v[238:239], off
	v_lshl_add_u64 v[238:239], s[14:15], 0, v[146:147]
	s_mov_b32 m0, s93
	s_nop 0
	global_load_lds_dwordx4 v[238:239], off
	s_waitcnt vmcnt(8)
	s_waitcnt lgkmcnt(0)
	s_barrier
; #define PG8_STAGE(bufoff, gbase, voff) do { _Pragma("unroll") for (int _i = 0; _i < 2; ++_i) \
;         __builtin_amdgcn_global_load_lds((const unsigned*)((const char*)(gbase) + (voff)[_i]), (LAS unsigned*)(lds + (bufoff) + ldsw + _i * 8192), 16, 0, 0); } while (0)
; #define PG8_LDA(dst, b, h) do { _Pragma("unroll") for (int m = 0; m < 4; ++m) _Pragma("unroll") for (int k = 0; k < 2; ++k) dst[m][k] = *(const LAS bf16x8*)(lds + PG8_SA(b, h) + aoff + m * 2048 + k * 1024); } while (0)
; #define PG8_LDB(dst, b, h) do { _Pragma("unroll") for (int n = 0; n < 2; ++n) _Pragma("unroll") for (int k = 0; k < 2; ++k) dst[n][k] = *(const LAS bf16x8*)(lds + PG8_SB(b, h) + boff + n * 2048 + k * 1024); } while (0)
; #define PG8_MMA(ai, bj, At, Bt) do { __builtin_amdgcn_s_setprio(1); _Pragma("unroll") for (int m = 0; m < 4; ++m) _Pragma("unroll") for (int n = 0; n < 2; ++n) _Pragma("unroll") for (int k = 0; k < 2; ++k) \
;         acc[ai][bj][m][n] = __builtin_amdgcn_mfma_f32_16x16x32_bf16(Bt[n][k], At[m][k], acc[ai][bj][m][n], 0, 0, 0); __builtin_amdgcn_s_setprio(0); } while (0)
; #define PG8_WAIT_V(n) asm volatile("s_waitcnt vmcnt(" #n ")" ::: "memory")
; #define PG8_WAIT_L(n) asm volatile("s_waitcnt lgkmcnt(" #n ")" ::: "memory")
; #define PG8_BAR __builtin_amdgcn_s_barrier()
; #define PG8_SCHED __builtin_amdgcn_sched_barrier(0)
; template <class Epi, class Sched, bool ALIGN_EPI = false, bool SP2 = false>
; __device__ __forceinline__ void gemm_phase(LAS unsigned char* lds, const Gemm g, const Sched& S, const Epi& E) {
;     ...
;         for (int t = 0; t < nt; t += 2) {
;             const bool last = (t == nt - 2);
;             const char* a1 = cA + (size_t)(t + 1) * kstep;
;             const char* a2 = last ? nA : cA + (size_t)(t + 2) * kstep; const char* b2 = last ? nB : cB + (size_t)(t + 2) * kstep;
;     ...
;             PG8_LDB(B0, 1, 0); PG8_LDB(B1, 1, 1); PG8_SCHED; PG8_LDA(At, 1, 0); PG8_STAGE(PG8_SA(0, 1), a2 + hstep, voffA);
;             PG8_WAIT_V(8); PG8_WAIT_L(0); PG8_BAR; PG8_MMA(0, 0, At, B0); PG8_MMA(0, 1, At, B1); PG8_BAR; PG8_SCHED;
;             PG8_LDA(At, 1, 1); PG8_STAGE(PG8_SB(1, 0), b3, voffB); PG8_STAGE(PG8_SB(1, 1), b3 + hstep, voffB); PG8_STAGE(PG8_SA(1, 0), a3, voffA);
;             PG8_WAIT_V(8); PG8_WAIT_L(0); PG8_BAR; PG8_MMA(1, 0, At, B0); PG8_MMA(1, 1, At, B1); PG8_BAR; PG8_SCHED;
	s_setprio 1
	s_waitcnt lgkmcnt(0)
	v_mfma_f32_16x16x32_bf16 v[124:127], v[128:131], v[182:185], v[124:127]
	v_mfma_f32_16x16x32_bf16 v[120:123], v[136:139], v[182:185], v[120:123]
	v_mfma_f32_16x16x32_bf16 v[108:111], v[128:131], v[190:193], v[108:111]
	v_mfma_f32_16x16x32_bf16 v[104:107], v[136:139], v[190:193], v[104:107]
	v_mfma_f32_16x16x32_bf16 v[92:95], v[128:131], v[198:201], v[92:95]
	v_mfma_f32_16x16x32_bf16 v[88:91], v[136:139], v[198:201], v[88:91]
	v_mfma_f32_16x16x32_bf16 v[76:79], v[128:131], v[222:225], v[76:79]
	v_mfma_f32_16x16x32_bf16 v[72:75], v[136:139], v[222:225], v[72:75]
	v_mfma_f32_16x16x32_bf16 v[124:127], v[132:135], v[186:189], v[124:127]
	v_mfma_f32_16x16x32_bf16 v[120:123], v[140:143], v[186:189], v[120:123]
	v_mfma_f32_16x16x32_bf16 v[108:111], v[132:135], v[194:197], v[108:111]
	v_mfma_f32_16x16x32_bf16 v[104:107], v[140:143], v[194:197], v[104:107]
	v_mfma_f32_16x16x32_bf16 v[92:95], v[132:135], v[202:205], v[92:95]
	v_mfma_f32_16x16x32_bf16 v[88:91], v[140:143], v[202:205], v[88:91]
	v_mfma_f32_16x16x32_bf16 v[76:79], v[132:135], v[226:229], v[76:79]
	v_mfma_f32_16x16x32_bf16 v[72:75], v[140:143], v[226:229], v[72:75]
	s_setprio 0
	s_setprio 1
	v_mfma_f32_16x16x32_bf16 v[116:119], v[166:169], v[182:185], v[116:119]
	v_mfma_f32_16x16x32_bf16 v[112:115], v[174:177], v[182:185], v[112:115]
	v_mfma_f32_16x16x32_bf16 v[100:103], v[166:169], v[190:193], v[100:103]
	v_mfma_f32_16x16x32_bf16 v[96:99], v[174:177], v[190:193], v[96:99]
	v_mfma_f32_16x16x32_bf16 v[84:87], v[166:169], v[198:201], v[84:87]
	v_mfma_f32_16x16x32_bf16 v[80:83], v[174:177], v[198:201], v[80:83]
	v_mfma_f32_16x16x32_bf16 v[68:71], v[166:169], v[222:225], v[68:71]
	v_mfma_f32_16x16x32_bf16 v[64:67], v[174:177], v[222:225], v[64:67]
	v_mfma_f32_16x16x32_bf16 v[116:119], v[170:173], v[186:189], v[116:119]
	v_mfma_f32_16x16x32_bf16 v[112:115], v[178:181], v[186:189], v[112:115]
	v_mfma_f32_16x16x32_bf16 v[100:103], v[170:173], v[194:197], v[100:103]
	v_mfma_f32_16x16x32_bf16 v[96:99], v[178:181], v[194:197], v[96:99]
	v_mfma_f32_16x16x32_bf16 v[84:87], v[170:173], v[202:205], v[84:87]
	v_mfma_f32_16x16x32_bf16 v[80:83], v[178:181], v[202:205], v[80:83]
	v_mfma_f32_16x16x32_bf16 v[68:71], v[170:173], v[226:229], v[68:71]
	v_mfma_f32_16x16x32_bf16 v[64:67], v[178:181], v[226:229], v[64:67]
	s_setprio 0
	s_barrier
	s_add_i32 s13, s13, s70
	v_lshl_add_u64 v[230:231], v[230:231], 0, s[30:31]
	s_mov_b32 m0, s13
	ds_read_b128 v[182:185], v221 offset:49152
	ds_read_b128 v[186:189], v221 offset:50176
	ds_read_b128 v[190:193], v221 offset:51200
	ds_read_b128 v[194:197], v221 offset:52224
	ds_read_b128 v[198:201], v221 offset:53248
	ds_read_b128 v[202:205], v221 offset:54272
	ds_read_b128 v[222:225], v221 offset:55296
	ds_read_b128 v[226:229], v221 offset:56320
	global_load_lds_dwordx4 v[230:231], off
	s_add_i32 m0, s13, 0x2000
	s_add_u32 s14, s36, 0x40080
	v_lshl_add_u64 v[230:231], v[232:233], 0, s[30:31]
	s_addc_u32 s15, s37, 0
	s_add_i32 s13, s16, s70
	global_load_lds_dwordx4 v[230:231], off
	s_waitcnt vmcnt(4)
	s_waitcnt lgkmcnt(0)
	s_barrier
	s_setprio 1
	s_waitcnt lgkmcnt(0)
	v_mfma_f32_16x16x32_bf16 v[60:63], v[128:131], v[182:185], v[60:63]
	v_mfma_f32_16x16x32_bf16 v[56:59], v[136:139], v[182:185], v[56:59]
	v_mfma_f32_16x16x32_bf16 v[44:47], v[128:131], v[190:193], v[44:47]
	v_lshl_add_u64 v[230:231], s[14:15], 0, v[148:149]
	s_mov_b32 m0, s13
	v_mfma_f32_16x16x32_bf16 v[40:43], v[136:139], v[190:193], v[40:43]
	global_load_lds_dwordx4 v[230:231], off
	v_mfma_f32_16x16x32_bf16 v[28:31], v[128:131], v[198:201], v[28:31]
	v_mfma_f32_16x16x32_bf16 v[24:27], v[136:139], v[198:201], v[24:27]
	v_mfma_f32_16x16x32_bf16 v[12:15], v[128:131], v[222:225], v[12:15]
	v_mfma_f32_16x16x32_bf16 v[8:11], v[136:139], v[222:225], v[8:11]
	v_mfma_f32_16x16x32_bf16 v[60:63], v[132:135], v[186:189], v[60:63]
	v_mfma_f32_16x16x32_bf16 v[56:59], v[140:143], v[186:189], v[56:59]
	v_lshl_add_u64 v[230:231], s[14:15], 0, v[144:145]
	s_add_i32 m0, s13, 0x2000
	v_mfma_f32_16x16x32_bf16 v[44:47], v[132:135], v[194:197], v[44:47]
	global_load_lds_dwordx4 v[230:231], off
	v_mfma_f32_16x16x32_bf16 v[40:43], v[140:143], v[194:197], v[40:43]
	v_mfma_f32_16x16x32_bf16 v[28:31], v[132:135], v[202:205], v[28:31]
	v_mfma_f32_16x16x32_bf16 v[24:27], v[140:143], v[202:205], v[24:27]
	v_mfma_f32_16x16x32_bf16 v[12:15], v[132:135], v[226:229], v[12:15]
	v_mfma_f32_16x16x32_bf16 v[8:11], v[140:143], v[226:229], v[8:11]
	s_setprio 0
	s_setprio 1
	v_mfma_f32_16x16x32_bf16 v[52:55], v[166:169], v[182:185], v[52:55]
	v_mfma_f32_16x16x32_bf16 v[48:51], v[174:177], v[182:185], v[48:51]
	v_lshl_add_u64 v[230:231], v[234:235], 0, s[30:31]
	s_mov_b32 m0, s96
	v_mfma_f32_16x16x32_bf16 v[36:39], v[166:169], v[190:193], v[36:39]
	global_load_lds_dwordx4 v[230:231], off
	v_mfma_f32_16x16x32_bf16 v[32:35], v[174:177], v[190:193], v[32:35]
	v_mfma_f32_16x16x32_bf16 v[20:23], v[166:169], v[198:201], v[20:23]
	v_mfma_f32_16x16x32_bf16 v[16:19], v[174:177], v[198:201], v[16:19]
	v_mfma_f32_16x16x32_bf16 v[4:7], v[166:169], v[222:225], v[4:7]
	v_mfma_f32_16x16x32_bf16 v[0:3], v[174:177], v[222:225], v[0:3]
	v_mfma_f32_16x16x32_bf16 v[52:55], v[170:173], v[186:189], v[52:55]
	v_mfma_f32_16x16x32_bf16 v[48:51], v[178:181], v[186:189], v[48:51]
	v_lshl_add_u64 v[230:231], v[236:237], 0, s[30:31]
	s_mov_b32 m0, s97
	v_mfma_f32_16x16x32_bf16 v[36:39], v[170:173], v[194:197], v[36:39]
	global_load_lds_dwordx4 v[230:231], off
	v_mfma_f32_16x16x32_bf16 v[32:35], v[178:181], v[194:197], v[32:35]
	v_mfma_f32_16x16x32_bf16 v[20:23], v[170:173], v[202:205], v[20:23]
	v_mfma_f32_16x16x32_bf16 v[16:19], v[178:181], v[202:205], v[16:19]
	v_mfma_f32_16x16x32_bf16 v[4:7], v[170:173], v[226:229], v[4:7]
	v_mfma_f32_16x16x32_bf16 v[0:3], v[178:181], v[226:229], v[0:3]
	s_setprio 0
	s_barrier
	s_add_i32 s12, s12, 2
	s_add_u32 s24, s24, 0x100
	s_addc_u32 s25, s25, 0
	s_add_u32 s10, s10, 0x100
	s_addc_u32 s11, s11, 0
	s_cmp_gt_u32 s12, 13
	s_cbranch_scc0 .LBB0_418
	s_and_b64 vcc, exec, s[50:51]
	s_cbranch_vccz .LBB0_421
	s_barrier

; #define PG8_STAGE(bufoff, gbase, voff) do { _Pragma("unroll") for (int _i = 0; _i < 2; ++_i) \
;         __builtin_amdgcn_global_load_lds((const unsigned*)((const char*)(gbase) + (voff)[_i]), (LAS unsigned*)(lds + (bufoff) + ldsw + _i * 8192), 16, 0, 0); } while (0)
; #define PG8_LDA(dst, b, h) do { _Pragma("unroll") for (int m = 0; m < 4; ++m) _Pragma("unroll") for (int k = 0; k < 2; ++k) dst[m][k] = *(const LAS bf16x8*)(lds + PG8_SA(b, h) + aoff + m * 2048 + k * 1024); } while (0)
; #define PG8_LDB(dst, b, h) do { _Pragma("unroll") for (int n = 0; n < 2; ++n) _Pragma("unroll") for (int k = 0; k < 2; ++k) dst[n][k] = *(const LAS bf16x8*)(lds + PG8_SB(b, h) + boff + n * 2048 + k * 1024); } while (0)
; #define PG8_MMA(ai, bj, At, Bt) do { __builtin_amdgcn_s_setprio(1); _Pragma("unroll") for (int m = 0; m < 4; ++m) _Pragma("unroll") for (int n = 0; n < 2; ++n) _Pragma("unroll") for (int k = 0; k < 2; ++k) \
;         acc[ai][bj][m][n] = __builtin_amdgcn_mfma_f32_16x16x32_bf16(Bt[n][k], At[m][k], acc[ai][bj][m][n], 0, 0, 0); __builtin_amdgcn_s_setprio(0); } while (0)
; #define PG8_WAIT_V(n) asm volatile("s_waitcnt vmcnt(" #n ")" ::: "memory")
; #define PG8_WAIT_L(n) asm volatile("s_waitcnt lgkmcnt(" #n ")" ::: "memory")
; template <class Epi, class Sched, bool ALIGN_EPI = false, bool SP2 = false>
; __device__ __forceinline__ void gemm_phase(LAS unsigned char* lds, const Gemm g, const Sched& S, const Epi& E) {
;     ...
;         for (int t = 0; t < nt; t += 2) {
;             const bool last = (t == nt - 2);
;             const char* a1 = cA + (size_t)(t + 1) * kstep;
;             const char* a2 = last ? nA : cA + (size_t)(t + 2) * kstep; const char* b2 = last ? nB : cB + (size_t)(t + 2) * kstep;
;             const char* a3 = a2 + kstep; const char* b3 = b2 + kstep;
;             if (last && has_next) S.a_ready(nxt);
;             if constexpr (SP2) {
;             PG8_LDB(B0, 0, 0); PG8_LDB(B1, 0, 1); PG8_SCHED; PG8_LDA(At, 0, 0); PG8_STAGE(PG8_SA(1, 1), a1 + hstep, voffA);
;             PG8_WAIT_V(8); PG8_WAIT_L(0); PG8_BAR; PG8_MMA(0, 0, At, B0); PG8_MMA(0, 1, At, B1); PG8_BAR; PG8_SCHED;
;             PG8_LDA(At, 0, 1); PG8_STAGE(PG8_SB(0, 0), b2, voffB); PG8_STAGE(PG8_SB(0, 1), b2 + hstep, voffB); PG8_STAGE(PG8_SA(0, 0), a2, voffA);
;             PG8_WAIT_V(8); PG8_WAIT_L(0); PG8_BAR; PG8_MMA(1, 0, At, B0); PG8_MMA(1, 1, At, B1); PG8_BAR; PG8_SCHED;
.LBB0_534:
	s_add_u32 s14, s46, 0xfffc0080
	s_addc_u32 s15, s47, -1
	s_add_i32 s16, 0, 0x10000
	s_cmp_eq_u32 s82, 12
	s_cselect_b32 s55, s39, s15
	s_cselect_b32 s54, s71, s14
	s_cselect_b32 s51, s37, s79
	s_cselect_b32 s50, s72, s73
	s_add_i32 s17, 0, 0x14000
	v_add_u32_e32 v140, s16, v194
	v_add_u32_e32 v180, s17, v194
	ds_read_b128 v[128:131], v140
	ds_read_b128 v[132:135], v140 offset:1024
	ds_read_b128 v[136:139], v140 offset:2048
	ds_read_b128 v[140:143], v140 offset:3072
	ds_read_b128 v[144:147], v180
	ds_read_b128 v[148:151], v180 offset:1024
	ds_read_b128 v[176:179], v180 offset:2048
	ds_read_b128 v[180:183], v180 offset:3072
	v_lshl_add_u64 v[234:235], s[46:47], 0, v[172:173]
	s_add_i32 m0, s7, 0xc000
	ds_read_b128 v[184:187], v196
	ds_read_b128 v[190:193], v196 offset:1024
	ds_read_b128 v[198:201], v196 offset:2048
	ds_read_b128 v[202:205], v196 offset:3072
	ds_read_b128 v[218:221], v196 offset:4096
	ds_read_b128 v[222:225], v196 offset:5120
	ds_read_b128 v[226:229], v196 offset:6144
	ds_read_b128 v[230:233], v196 offset:7168
	global_load_lds_dwordx4 v[234:235], off
	v_lshl_add_u64 v[234:235], s[46:47], 0, v[174:175]
	s_add_i32 m0, s7, 0xe000
	s_nop 0
	global_load_lds_dwordx4 v[234:235], off
	s_waitcnt vmcnt(8)
	s_waitcnt lgkmcnt(0)
	s_barrier
	s_setprio 1
	s_waitcnt lgkmcnt(0)
	v_mfma_f32_16x16x32_bf16 v[124:127], v[128:131], v[184:187], v[124:127]
	v_mfma_f32_16x16x32_bf16 v[120:123], v[136:139], v[184:187], v[120:123]
	v_mfma_f32_16x16x32_bf16 v[108:111], v[128:131], v[198:201], v[108:111]
	v_mfma_f32_16x16x32_bf16 v[104:107], v[136:139], v[198:201], v[104:107]
	v_mfma_f32_16x16x32_bf16 v[92:95], v[128:131], v[218:221], v[92:95]
	v_mfma_f32_16x16x32_bf16 v[88:91], v[136:139], v[218:221], v[88:91]
	v_mfma_f32_16x16x32_bf16 v[76:79], v[128:131], v[226:229], v[76:79]
	v_mfma_f32_16x16x32_bf16 v[72:75], v[136:139], v[226:229], v[72:75]
	v_mfma_f32_16x16x32_bf16 v[124:127], v[132:135], v[190:193], v[124:127]
	v_mfma_f32_16x16x32_bf16 v[120:123], v[140:143], v[190:193], v[120:123]
	v_mfma_f32_16x16x32_bf16 v[108:111], v[132:135], v[202:205], v[108:111]
	v_mfma_f32_16x16x32_bf16 v[104:107], v[140:143], v[202:205], v[104:107]
	v_mfma_f32_16x16x32_bf16 v[92:95], v[132:135], v[222:225], v[92:95]
	v_mfma_f32_16x16x32_bf16 v[88:91], v[140:143], v[222:225], v[88:91]
	v_mfma_f32_16x16x32_bf16 v[76:79], v[132:135], v[230:233], v[76:79]
	v_mfma_f32_16x16x32_bf16 v[72:75], v[140:143], v[230:233], v[72:75]
	s_setprio 0
	s_setprio 1
	v_mfma_f32_16x16x32_bf16 v[116:119], v[144:147], v[184:187], v[116:119]
	v_mfma_f32_16x16x32_bf16 v[112:115], v[176:179], v[184:187], v[112:115]
	v_mfma_f32_16x16x32_bf16 v[100:103], v[144:147], v[198:201], v[100:103]
	v_mfma_f32_16x16x32_bf16 v[96:99], v[176:179], v[198:201], v[96:99]
	v_mfma_f32_16x16x32_bf16 v[84:87], v[144:147], v[218:221], v[84:87]
	v_mfma_f32_16x16x32_bf16 v[80:83], v[176:179], v[218:221], v[80:83]
	v_mfma_f32_16x16x32_bf16 v[68:71], v[144:147], v[226:229], v[68:71]
	v_mfma_f32_16x16x32_bf16 v[64:67], v[176:179], v[226:229], v[64:67]
	v_mfma_f32_16x16x32_bf16 v[116:119], v[148:151], v[190:193], v[116:119]
	v_mfma_f32_16x16x32_bf16 v[112:115], v[180:183], v[190:193], v[112:115]
	v_mfma_f32_16x16x32_bf16 v[100:103], v[148:151], v[202:205], v[100:103]
	v_mfma_f32_16x16x32_bf16 v[96:99], v[180:183], v[202:205], v[96:99]
	v_mfma_f32_16x16x32_bf16 v[84:87], v[148:151], v[222:225], v[84:87]
	v_mfma_f32_16x16x32_bf16 v[80:83], v[180:183], v[222:225], v[80:83]
	v_mfma_f32_16x16x32_bf16 v[68:71], v[148:151], v[230:233], v[68:71]
	v_mfma_f32_16x16x32_bf16 v[64:67], v[180:183], v[230:233], v[64:67]
	s_setprio 0
	s_barrier
	s_add_i32 s14, s16, s6
	v_lshl_add_u64 v[234:235], s[50:51], 0, v[166:167]
	s_mov_b32 m0, s14
	ds_read_b128 v[184:187], v196 offset:16384
	ds_read_b128 v[190:193], v196 offset:17408
	ds_read_b128 v[198:201], v196 offset:18432
	ds_read_b128 v[202:205], v196 offset:19456
	ds_read_b128 v[218:221], v196 offset:20480
	ds_read_b128 v[222:225], v196 offset:21504
	ds_read_b128 v[226:229], v196 offset:22528
	ds_read_b128 v[230:233], v196 offset:23552
	global_load_lds_dwordx4 v[234:235], off
	s_add_i32 m0, s14, 0x2000
	s_add_u32 s14, s50, 0x40000
	v_lshl_add_u64 v[236:237], s[50:51], 0, v[162:163]
	s_addc_u32 s15, s51, 0
	s_add_i32 s16, s17, s6
	global_load_lds_dwordx4 v[236:237], off
	s_waitcnt vmcnt(4)
	s_waitcnt lgkmcnt(0)
	s_barrier
; #define PG8_STAGE(bufoff, gbase, voff) do { _Pragma("unroll") for (int _i = 0; _i < 2; ++_i) \
;         __builtin_amdgcn_global_load_lds((const unsigned*)((const char*)(gbase) + (voff)[_i]), (LAS unsigned*)(lds + (bufoff) + ldsw + _i * 8192), 16, 0, 0); } while (0)
; #define PG8_LDA(dst, b, h) do { _Pragma("unroll") for (int m = 0; m < 4; ++m) _Pragma("unroll") for (int k = 0; k < 2; ++k) dst[m][k] = *(const LAS bf16x8*)(lds + PG8_SA(b, h) + aoff + m * 2048 + k * 1024); } while (0)
; #define PG8_LDB(dst, b, h) do { _Pragma("unroll") for (int n = 0; n < 2; ++n) _Pragma("unroll") for (int k = 0; k < 2; ++k) dst[n][k] = *(const LAS bf16x8*)(lds + PG8_SB(b, h) + boff + n * 2048 + k * 1024); } while (0)
; #define PG8_MMA(ai, bj, At, Bt) do { __builtin_amdgcn_s_setprio(1); _Pragma("unroll") for (int m = 0; m < 4; ++m) _Pragma("unroll") for (int n = 0; n < 2; ++n) _Pragma("unroll") for (int k = 0; k < 2; ++k) \
;         acc[ai][bj][m][n] = __builtin_amdgcn_mfma_f32_16x16x32_bf16(Bt[n][k], At[m][k], acc[ai][bj][m][n], 0, 0, 0); __builtin_amdgcn_s_setprio(0); } while (0)
; #define PG8_WAIT_V(n) asm volatile("s_waitcnt vmcnt(" #n ")" ::: "memory")
; #define PG8_WAIT_L(n) asm volatile("s_waitcnt lgkmcnt(" #n ")" ::: "memory")
; #define PG8_BAR __builtin_amdgcn_s_barrier()
; #define PG8_SCHED __builtin_amdgcn_sched_barrier(0)
; template <class Epi, class Sched, bool ALIGN_EPI = false, bool SP2 = false>
; __device__ __forceinline__ void gemm_phase(LAS unsigned char* lds, const Gemm g, const Sched& S, const Epi& E) {
;     ...
;             PG8_WAIT_V(8); PG8_WAIT_L(0); PG8_BAR; PG8_MMA(1, 0, At, B0); PG8_MMA(1, 1, At, B1); PG8_BAR; PG8_SCHED;
;             PG8_LDB(B0, 1, 0); PG8_LDB(B1, 1, 1); PG8_SCHED; PG8_LDA(At, 1, 0); PG8_STAGE(PG8_SA(0, 1), a2 + hstep, voffA);
;             PG8_WAIT_V(8); PG8_WAIT_L(0); PG8_BAR; PG8_MMA(0, 0, At, B0); PG8_MMA(0, 1, At, B1); PG8_BAR; PG8_SCHED;
	s_setprio 1
	s_waitcnt lgkmcnt(0)
	v_mfma_f32_16x16x32_bf16 v[60:63], v[128:131], v[184:187], v[60:63]
	v_mfma_f32_16x16x32_bf16 v[56:59], v[136:139], v[184:187], v[56:59]
	v_mfma_f32_16x16x32_bf16 v[44:47], v[128:131], v[198:201], v[44:47]
	v_lshl_add_u64 v[238:239], s[14:15], 0, v[166:167]
	s_mov_b32 m0, s16
	v_lshl_add_u64 v[240:241], s[54:55], 0, v[164:165]
	v_mfma_f32_16x16x32_bf16 v[40:43], v[136:139], v[198:201], v[40:43]
	global_load_lds_dwordx4 v[238:239], off
	v_mfma_f32_16x16x32_bf16 v[28:31], v[128:131], v[218:221], v[28:31]
	v_mfma_f32_16x16x32_bf16 v[24:27], v[136:139], v[218:221], v[24:27]
	v_mfma_f32_16x16x32_bf16 v[12:15], v[128:131], v[226:229], v[12:15]
	v_mfma_f32_16x16x32_bf16 v[8:11], v[136:139], v[226:229], v[8:11]
	v_mfma_f32_16x16x32_bf16 v[60:63], v[132:135], v[190:193], v[60:63]
	v_mfma_f32_16x16x32_bf16 v[56:59], v[140:143], v[190:193], v[56:59]
	v_lshl_add_u64 v[238:239], s[14:15], 0, v[162:163]
	s_add_i32 m0, s16, 0x2000
	v_mfma_f32_16x16x32_bf16 v[44:47], v[132:135], v[202:205], v[44:47]
	global_load_lds_dwordx4 v[238:239], off
	v_mfma_f32_16x16x32_bf16 v[40:43], v[140:143], v[202:205], v[40:43]
	v_mfma_f32_16x16x32_bf16 v[28:31], v[132:135], v[222:225], v[28:31]
	v_mfma_f32_16x16x32_bf16 v[24:27], v[140:143], v[222:225], v[24:27]
	v_mfma_f32_16x16x32_bf16 v[12:15], v[132:135], v[230:233], v[12:15]
	v_mfma_f32_16x16x32_bf16 v[8:11], v[140:143], v[230:233], v[8:11]
	s_setprio 0
	s_setprio 1
	v_mfma_f32_16x16x32_bf16 v[52:55], v[144:147], v[184:187], v[52:55]
	v_mfma_f32_16x16x32_bf16 v[48:51], v[176:179], v[184:187], v[48:51]
	v_lshl_add_u64 v[238:239], s[54:55], 0, v[168:169]
	s_mov_b32 m0, s7
	v_mfma_f32_16x16x32_bf16 v[36:39], v[144:147], v[198:201], v[36:39]
	global_load_lds_dwordx4 v[238:239], off
	v_mfma_f32_16x16x32_bf16 v[32:35], v[176:179], v[198:201], v[32:35]
	v_mfma_f32_16x16x32_bf16 v[20:23], v[144:147], v[218:221], v[20:23]
	v_mfma_f32_16x16x32_bf16 v[16:19], v[176:179], v[218:221], v[16:19]
	v_mfma_f32_16x16x32_bf16 v[4:7], v[144:147], v[226:229], v[4:7]
	v_mfma_f32_16x16x32_bf16 v[0:3], v[176:179], v[226:229], v[0:3]
	v_mfma_f32_16x16x32_bf16 v[52:55], v[148:151], v[190:193], v[52:55]
	v_mfma_f32_16x16x32_bf16 v[48:51], v[180:183], v[190:193], v[48:51]
	s_mov_b32 m0, s8
	v_mfma_f32_16x16x32_bf16 v[36:39], v[148:151], v[202:205], v[36:39]
	global_load_lds_dwordx4 v[240:241], off
	v_mfma_f32_16x16x32_bf16 v[32:35], v[180:183], v[202:205], v[32:35]
	v_mfma_f32_16x16x32_bf16 v[20:23], v[148:151], v[222:225], v[20:23]
	v_mfma_f32_16x16x32_bf16 v[16:19], v[180:183], v[222:225], v[16:19]
	v_mfma_f32_16x16x32_bf16 v[4:7], v[148:151], v[230:233], v[4:7]
	v_mfma_f32_16x16x32_bf16 v[0:3], v[180:183], v[230:233], v[0:3]
	s_setprio 0
	s_barrier
	s_add_i32 s16, 0, 0x18000
	s_add_i32 s17, 0, 0x1c000
	v_add_u32_e32 v140, s16, v194
	v_add_u32_e32 v180, s17, v194
	ds_read_b128 v[128:131], v140
	ds_read_b128 v[132:135], v140 offset:1024
	ds_read_b128 v[136:139], v140 offset:2048
	ds_read_b128 v[140:143], v140 offset:3072
	ds_read_b128 v[144:147], v180
	ds_read_b128 v[148:151], v180 offset:1024
	ds_read_b128 v[176:179], v180 offset:2048
	ds_read_b128 v[180:183], v180 offset:3072
	s_add_u32 s14, s54, 0x40000
	s_addc_u32 s15, s55, 0
	s_mov_b32 m0, s9
	v_lshl_add_u64 v[242:243], s[14:15], 0, v[168:169]
	ds_read_b128 v[184:187], v196 offset:32768
	ds_read_b128 v[190:193], v196 offset:33792
	ds_read_b128 v[198:201], v196 offset:34816
	ds_read_b128 v[202:205], v196 offset:35840
	ds_read_b128 v[218:221], v196 offset:36864
	ds_read_b128 v[222:225], v196 offset:37888
	ds_read_b128 v[226:229], v196 offset:38912
	ds_read_b128 v[230:233], v196 offset:39936
	global_load_lds_dwordx4 v[242:243], off
	v_lshl_add_u64 v[242:243], s[14:15], 0, v[164:165]
	s_mov_b32 m0, s10
	s_nop 0
	global_load_lds_dwordx4 v[242:243], off
	s_waitcnt vmcnt(8)
	s_waitcnt lgkmcnt(0)
	s_barrier
; #define PG8_STAGE(bufoff, gbase, voff) do { _Pragma("unroll") for (int _i = 0; _i < 2; ++_i) \
;         __builtin_amdgcn_global_load_lds((const unsigned*)((const char*)(gbase) + (voff)[_i]), (LAS unsigned*)(lds + (bufoff) + ldsw + _i * 8192), 16, 0, 0); } while (0)
; #define PG8_LDA(dst, b, h) do { _Pragma("unroll") for (int m = 0; m < 4; ++m) _Pragma("unroll") for (int k = 0; k < 2; ++k) dst[m][k] = *(const LAS bf16x8*)(lds + PG8_SA(b, h) + aoff + m * 2048 + k * 1024); } while (0)
; #define PG8_MMA(ai, bj, At, Bt) do { __builtin_amdgcn_s_setprio(1); _Pragma("unroll") for (int m = 0; m < 4; ++m) _Pragma("unroll") for (int n = 0; n < 2; ++n) _Pragma("unroll") for (int k = 0; k < 2; ++k) \
;         acc[ai][bj][m][n] = __builtin_amdgcn_mfma_f32_16x16x32_bf16(Bt[n][k], At[m][k], acc[ai][bj][m][n], 0, 0, 0); __builtin_amdgcn_s_setprio(0); } while (0)
; #define PG8_WAIT_V(n) asm volatile("s_waitcnt vmcnt(" #n ")" ::: "memory")
; #define PG8_WAIT_L(n) asm volatile("s_waitcnt lgkmcnt(" #n ")" ::: "memory")
; #define PG8_BAR __builtin_amdgcn_s_barrier()
; #define PG8_SCHED __builtin_amdgcn_sched_barrier(0)
; template <class Epi, class Sched, bool ALIGN_EPI = false, bool SP2 = false>
; __device__ __forceinline__ void gemm_phase(LAS unsigned char* lds, const Gemm g, const Sched& S, const Epi& E) {
;     ...
;         for (int t = 0; t < nt; t += 2) {
;     ...
;             PG8_WAIT_V(8); PG8_WAIT_L(0); PG8_BAR; PG8_MMA(0, 0, At, B0); PG8_MMA(0, 1, At, B1); PG8_BAR; PG8_SCHED;
;             PG8_LDA(At, 1, 1); PG8_STAGE(PG8_SB(1, 0), b3, voffB); PG8_STAGE(PG8_SB(1, 1), b3 + hstep, voffB); PG8_STAGE(PG8_SA(1, 0), a3, voffA);
;             PG8_WAIT_V(8); PG8_WAIT_L(0); PG8_BAR; PG8_MMA(1, 0, At, B0); PG8_MMA(1, 1, At, B1); PG8_BAR; PG8_SCHED;
	s_setprio 1
	s_waitcnt lgkmcnt(0)
	v_mfma_f32_16x16x32_bf16 v[124:127], v[128:131], v[184:187], v[124:127]
	v_mfma_f32_16x16x32_bf16 v[120:123], v[136:139], v[184:187], v[120:123]
	v_mfma_f32_16x16x32_bf16 v[108:111], v[128:131], v[198:201], v[108:111]
	v_mfma_f32_16x16x32_bf16 v[104:107], v[136:139], v[198:201], v[104:107]
	v_mfma_f32_16x16x32_bf16 v[92:95], v[128:131], v[218:221], v[92:95]
	v_mfma_f32_16x16x32_bf16 v[88:91], v[136:139], v[218:221], v[88:91]
	v_mfma_f32_16x16x32_bf16 v[76:79], v[128:131], v[226:229], v[76:79]
	v_mfma_f32_16x16x32_bf16 v[72:75], v[136:139], v[226:229], v[72:75]
	v_mfma_f32_16x16x32_bf16 v[124:127], v[132:135], v[190:193], v[124:127]
	v_mfma_f32_16x16x32_bf16 v[120:123], v[140:143], v[190:193], v[120:123]
	v_mfma_f32_16x16x32_bf16 v[108:111], v[132:135], v[202:205], v[108:111]
	v_mfma_f32_16x16x32_bf16 v[104:107], v[140:143], v[202:205], v[104:107]
	v_mfma_f32_16x16x32_bf16 v[92:95], v[132:135], v[222:225], v[92:95]
	v_mfma_f32_16x16x32_bf16 v[88:91], v[140:143], v[222:225], v[88:91]
	v_mfma_f32_16x16x32_bf16 v[76:79], v[132:135], v[230:233], v[76:79]
	v_mfma_f32_16x16x32_bf16 v[72:75], v[140:143], v[230:233], v[72:75]
	s_setprio 0
	s_setprio 1
	v_mfma_f32_16x16x32_bf16 v[116:119], v[144:147], v[184:187], v[116:119]
	v_mfma_f32_16x16x32_bf16 v[112:115], v[176:179], v[184:187], v[112:115]
	v_mfma_f32_16x16x32_bf16 v[100:103], v[144:147], v[198:201], v[100:103]
	v_mfma_f32_16x16x32_bf16 v[96:99], v[176:179], v[198:201], v[96:99]
	v_mfma_f32_16x16x32_bf16 v[84:87], v[144:147], v[218:221], v[84:87]
	v_mfma_f32_16x16x32_bf16 v[80:83], v[176:179], v[218:221], v[80:83]
	v_mfma_f32_16x16x32_bf16 v[68:71], v[144:147], v[226:229], v[68:71]
	v_mfma_f32_16x16x32_bf16 v[64:67], v[176:179], v[226:229], v[64:67]
	v_mfma_f32_16x16x32_bf16 v[116:119], v[148:151], v[190:193], v[116:119]
	v_mfma_f32_16x16x32_bf16 v[112:115], v[180:183], v[190:193], v[112:115]
	v_mfma_f32_16x16x32_bf16 v[100:103], v[148:151], v[202:205], v[100:103]
	v_mfma_f32_16x16x32_bf16 v[96:99], v[180:183], v[202:205], v[96:99]
	v_mfma_f32_16x16x32_bf16 v[84:87], v[148:151], v[222:225], v[84:87]
	v_mfma_f32_16x16x32_bf16 v[80:83], v[180:183], v[222:225], v[80:83]
	v_mfma_f32_16x16x32_bf16 v[68:71], v[148:151], v[230:233], v[68:71]
	v_mfma_f32_16x16x32_bf16 v[64:67], v[180:183], v[230:233], v[64:67]
	s_setprio 0
	s_barrier
	s_add_i32 s14, s16, s6
	v_lshl_add_u64 v[234:235], v[234:235], 0, s[30:31]
	s_mov_b32 m0, s14
	ds_read_b128 v[184:187], v196 offset:49152
	ds_read_b128 v[190:193], v196 offset:50176
	ds_read_b128 v[198:201], v196 offset:51200
	ds_read_b128 v[202:205], v196 offset:52224
	ds_read_b128 v[218:221], v196 offset:53248
	ds_read_b128 v[222:225], v196 offset:54272
	ds_read_b128 v[226:229], v196 offset:55296
	ds_read_b128 v[230:233], v196 offset:56320
	global_load_lds_dwordx4 v[234:235], off
	s_add_i32 m0, s14, 0x2000
	s_add_u32 s14, s50, 0x40080
	v_lshl_add_u64 v[234:235], v[236:237], 0, s[30:31]
	s_addc_u32 s15, s51, 0
	s_add_i32 s16, s17, s6
	global_load_lds_dwordx4 v[234:235], off
	s_waitcnt vmcnt(4)
	s_waitcnt lgkmcnt(0)
	s_barrier
	s_setprio 1
	s_waitcnt lgkmcnt(0)
	v_mfma_f32_16x16x32_bf16 v[60:63], v[128:131], v[184:187], v[60:63]
	v_mfma_f32_16x16x32_bf16 v[56:59], v[136:139], v[184:187], v[56:59]
	v_mfma_f32_16x16x32_bf16 v[44:47], v[128:131], v[198:201], v[44:47]
	v_lshl_add_u64 v[234:235], s[14:15], 0, v[166:167]
	s_mov_b32 m0, s16
	v_mfma_f32_16x16x32_bf16 v[40:43], v[136:139], v[198:201], v[40:43]
	global_load_lds_dwordx4 v[234:235], off
	v_mfma_f32_16x16x32_bf16 v[28:31], v[128:131], v[218:221], v[28:31]
	v_mfma_f32_16x16x32_bf16 v[24:27], v[136:139], v[218:221], v[24:27]
	v_mfma_f32_16x16x32_bf16 v[12:15], v[128:131], v[226:229], v[12:15]
	v_mfma_f32_16x16x32_bf16 v[8:11], v[136:139], v[226:229], v[8:11]
	v_mfma_f32_16x16x32_bf16 v[60:63], v[132:135], v[190:193], v[60:63]
	v_mfma_f32_16x16x32_bf16 v[56:59], v[140:143], v[190:193], v[56:59]
	v_lshl_add_u64 v[234:235], s[14:15], 0, v[162:163]
	s_add_i32 m0, s16, 0x2000
	v_mfma_f32_16x16x32_bf16 v[44:47], v[132:135], v[202:205], v[44:47]
	global_load_lds_dwordx4 v[234:235], off
	v_mfma_f32_16x16x32_bf16 v[40:43], v[140:143], v[202:205], v[40:43]
	v_mfma_f32_16x16x32_bf16 v[28:31], v[132:135], v[222:225], v[28:31]
	v_mfma_f32_16x16x32_bf16 v[24:27], v[140:143], v[222:225], v[24:27]
	v_mfma_f32_16x16x32_bf16 v[12:15], v[132:135], v[230:233], v[12:15]
	v_mfma_f32_16x16x32_bf16 v[8:11], v[140:143], v[230:233], v[8:11]
	s_setprio 0
	s_setprio 1
	v_mfma_f32_16x16x32_bf16 v[52:55], v[144:147], v[184:187], v[52:55]
	v_mfma_f32_16x16x32_bf16 v[48:51], v[176:179], v[184:187], v[48:51]
	v_lshl_add_u64 v[234:235], v[238:239], 0, s[30:31]
	s_mov_b32 m0, s11
	v_mfma_f32_16x16x32_bf16 v[36:39], v[144:147], v[198:201], v[36:39]
	global_load_lds_dwordx4 v[234:235], off
	v_mfma_f32_16x16x32_bf16 v[32:35], v[176:179], v[198:201], v[32:35]
	v_mfma_f32_16x16x32_bf16 v[20:23], v[144:147], v[218:221], v[20:23]
	v_mfma_f32_16x16x32_bf16 v[16:19], v[176:179], v[218:221], v[16:19]
	v_mfma_f32_16x16x32_bf16 v[4:7], v[144:147], v[226:229], v[4:7]
	v_mfma_f32_16x16x32_bf16 v[0:3], v[176:179], v[226:229], v[0:3]
	v_mfma_f32_16x16x32_bf16 v[52:55], v[148:151], v[190:193], v[52:55]
	v_mfma_f32_16x16x32_bf16 v[48:51], v[180:183], v[190:193], v[48:51]
	v_lshl_add_u64 v[234:235], v[240:241], 0, s[30:31]
	s_mov_b32 m0, s12
	v_mfma_f32_16x16x32_bf16 v[36:39], v[148:151], v[202:205], v[36:39]
	global_load_lds_dwordx4 v[234:235], off
	v_mfma_f32_16x16x32_bf16 v[32:35], v[180:183], v[202:205], v[32:35]
	v_mfma_f32_16x16x32_bf16 v[20:23], v[148:151], v[222:225], v[20:23]
	v_mfma_f32_16x16x32_bf16 v[16:19], v[180:183], v[222:225], v[16:19]
	v_mfma_f32_16x16x32_bf16 v[4:7], v[148:151], v[230:233], v[4:7]
	v_mfma_f32_16x16x32_bf16 v[0:3], v[180:183], v[230:233], v[0:3]
	s_setprio 0
	s_barrier
	s_add_i32 s82, s82, 2
	s_add_u32 s46, s46, 0x100
	s_addc_u32 s47, s47, 0
	s_add_u32 s73, s73, 0x100
	s_addc_u32 s79, s79, 0
	s_cmp_gt_u32 s82, 13
	s_cbranch_scc0 .LBB0_534
	s_and_b64 vcc, exec, s[28:29]
	s_cbranch_vccz .LBB0_537
	s_barrier

; #define PG8_STAGE(bufoff, gbase, voff) do { _Pragma("unroll") for (int _i = 0; _i < 2; ++_i) \
;         __builtin_amdgcn_global_load_lds((const unsigned*)((const char*)(gbase) + (voff)[_i]), (LAS unsigned*)(lds + (bufoff) + ldsw + _i * 8192), 16, 0, 0); } while (0)
; #define PG8_LDA(dst, b, h) do { _Pragma("unroll") for (int m = 0; m < 4; ++m) _Pragma("unroll") for (int k = 0; k < 2; ++k) dst[m][k] = *(const LAS bf16x8*)(lds + PG8_SA(b, h) + aoff + m * 2048 + k * 1024); } while (0)
; #define PG8_LDB(dst, b, h) do { _Pragma("unroll") for (int n = 0; n < 2; ++n) _Pragma("unroll") for (int k = 0; k < 2; ++k) dst[n][k] = *(const LAS bf16x8*)(lds + PG8_SB(b, h) + boff + n * 2048 + k * 1024); } while (0)
; #define PG8_MMA(ai, bj, At, Bt) do { __builtin_amdgcn_s_setprio(1); _Pragma("unroll") for (int m = 0; m < 4; ++m) _Pragma("unroll") for (int n = 0; n < 2; ++n) _Pragma("unroll") for (int k = 0; k < 2; ++k) \
;         acc[ai][bj][m][n] = __builtin_amdgcn_mfma_f32_16x16x32_bf16(Bt[n][k], At[m][k], acc[ai][bj][m][n], 0, 0, 0); __builtin_amdgcn_s_setprio(0); } while (0)
; #define PG8_WAIT_V(n) asm volatile("s_waitcnt vmcnt(" #n ")" ::: "memory")
; #define PG8_WAIT_L(n) asm volatile("s_waitcnt lgkmcnt(" #n ")" ::: "memory")
; template <class Epi, class Sched, bool ALIGN_EPI = false, bool SP2 = false>
; __device__ __forceinline__ void gemm_phase(LAS unsigned char* lds, const Gemm g, const Sched& S, const Epi& E) {
;     ...
;         for (int t = 0; t < nt; t += 2) {
;             const bool last = (t == nt - 2);
;             const char* a1 = cA + (size_t)(t + 1) * kstep;
;             const char* a2 = last ? nA : cA + (size_t)(t + 2) * kstep; const char* b2 = last ? nB : cB + (size_t)(t + 2) * kstep;
;             const char* a3 = a2 + kstep; const char* b3 = b2 + kstep;
;             if (last && has_next) S.a_ready(nxt);
;             if constexpr (SP2) {
;             PG8_LDB(B0, 0, 0); PG8_LDB(B1, 0, 1); PG8_SCHED; PG8_LDA(At, 0, 0); PG8_STAGE(PG8_SA(1, 1), a1 + hstep, voffA);
;             PG8_WAIT_V(8); PG8_WAIT_L(0); PG8_BAR; PG8_MMA(0, 0, At, B0); PG8_MMA(0, 1, At, B1); PG8_BAR; PG8_SCHED;
;             PG8_LDA(At, 0, 1); PG8_STAGE(PG8_SB(0, 0), b2, voffB); PG8_STAGE(PG8_SB(0, 1), b2 + hstep, voffB); PG8_STAGE(PG8_SA(0, 0), a2, voffA);
;             PG8_WAIT_V(8); PG8_WAIT_L(0); PG8_BAR; PG8_MMA(1, 0, At, B0); PG8_MMA(1, 1, At, B1); PG8_BAR; PG8_SCHED;
.LBB0_612:
	s_add_u32 s14, s42, 0xfff00080
	s_addc_u32 s15, s43, -1
	s_add_i32 s16, 0, 0x10000
	s_cmp_eq_u32 s71, 60
	s_cselect_b32 s49, s37, s15
	s_cselect_b32 s48, s54, s14
	s_cselect_b32 s47, s29, s65
	s_cselect_b32 s46, s55, s64
	s_add_i32 s17, 0, 0x14000
	v_add_u32_e32 v140, s16, v175
	v_add_u32_e32 v172, s17, v175
	ds_read_b128 v[128:131], v140
	ds_read_b128 v[132:135], v140 offset:1024
	ds_read_b128 v[136:139], v140 offset:2048
	ds_read_b128 v[140:143], v140 offset:3072
	ds_read_b128 v[164:167], v172
	ds_read_b128 v[168:171], v172 offset:1024
	ds_read_b128 v[180:183], v172 offset:2048
	ds_read_b128 v[184:187], v172 offset:3072
	v_lshl_add_u64 v[172:173], s[42:43], 0, v[150:151]
	s_add_i32 m0, s7, 0xc000
	ds_read_b128 v[188:191], v178
	ds_read_b128 v[192:195], v178 offset:1024
	ds_read_b128 v[196:199], v178 offset:2048
	ds_read_b128 v[200:203], v178 offset:3072
	ds_read_b128 v[218:221], v178 offset:4096
	ds_read_b128 v[222:225], v178 offset:5120
	ds_read_b128 v[226:229], v178 offset:6144
	ds_read_b128 v[230:233], v178 offset:7168
	global_load_lds_dwordx4 v[172:173], off
	v_lshl_add_u64 v[172:173], s[42:43], 0, v[162:163]
	s_add_i32 m0, s7, 0xe000
	s_nop 0
	global_load_lds_dwordx4 v[172:173], off
	s_waitcnt vmcnt(8)
	s_waitcnt lgkmcnt(0)
	s_barrier
	s_setprio 1
	s_waitcnt lgkmcnt(0)
	v_mfma_f32_16x16x32_bf16 v[124:127], v[128:131], v[188:191], v[124:127]
	v_mfma_f32_16x16x32_bf16 v[120:123], v[136:139], v[188:191], v[120:123]
	v_mfma_f32_16x16x32_bf16 v[112:115], v[128:131], v[196:199], v[112:115]
	v_mfma_f32_16x16x32_bf16 v[104:107], v[136:139], v[196:199], v[104:107]
	v_mfma_f32_16x16x32_bf16 v[92:95], v[128:131], v[218:221], v[92:95]
	v_mfma_f32_16x16x32_bf16 v[88:91], v[136:139], v[218:221], v[88:91]
	v_mfma_f32_16x16x32_bf16 v[76:79], v[128:131], v[226:229], v[76:79]
	v_mfma_f32_16x16x32_bf16 v[72:75], v[136:139], v[226:229], v[72:75]
	v_mfma_f32_16x16x32_bf16 v[124:127], v[132:135], v[192:195], v[124:127]
	v_mfma_f32_16x16x32_bf16 v[120:123], v[140:143], v[192:195], v[120:123]
	v_mfma_f32_16x16x32_bf16 v[112:115], v[132:135], v[200:203], v[112:115]
	v_mfma_f32_16x16x32_bf16 v[104:107], v[140:143], v[200:203], v[104:107]
	v_mfma_f32_16x16x32_bf16 v[92:95], v[132:135], v[222:225], v[92:95]
	v_mfma_f32_16x16x32_bf16 v[88:91], v[140:143], v[222:225], v[88:91]
	v_mfma_f32_16x16x32_bf16 v[76:79], v[132:135], v[230:233], v[76:79]
	v_mfma_f32_16x16x32_bf16 v[72:75], v[140:143], v[230:233], v[72:75]
	s_setprio 0
	s_setprio 1
	v_mfma_f32_16x16x32_bf16 v[116:119], v[164:167], v[188:191], v[116:119]
	v_mfma_f32_16x16x32_bf16 v[108:111], v[180:183], v[188:191], v[108:111]
	v_mfma_f32_16x16x32_bf16 v[100:103], v[164:167], v[196:199], v[100:103]
	v_mfma_f32_16x16x32_bf16 v[96:99], v[180:183], v[196:199], v[96:99]
	v_mfma_f32_16x16x32_bf16 v[84:87], v[164:167], v[218:221], v[84:87]
	v_mfma_f32_16x16x32_bf16 v[80:83], v[180:183], v[218:221], v[80:83]
	v_mfma_f32_16x16x32_bf16 v[68:71], v[164:167], v[226:229], v[68:71]
	v_mfma_f32_16x16x32_bf16 v[64:67], v[180:183], v[226:229], v[64:67]
	v_mfma_f32_16x16x32_bf16 v[116:119], v[168:171], v[192:195], v[116:119]
	v_mfma_f32_16x16x32_bf16 v[108:111], v[184:187], v[192:195], v[108:111]
	v_mfma_f32_16x16x32_bf16 v[100:103], v[168:171], v[200:203], v[100:103]
	v_mfma_f32_16x16x32_bf16 v[96:99], v[184:187], v[200:203], v[96:99]
	v_mfma_f32_16x16x32_bf16 v[84:87], v[168:171], v[222:225], v[84:87]
	v_mfma_f32_16x16x32_bf16 v[80:83], v[184:187], v[222:225], v[80:83]
	v_mfma_f32_16x16x32_bf16 v[68:71], v[168:171], v[230:233], v[68:71]
	v_mfma_f32_16x16x32_bf16 v[64:67], v[184:187], v[230:233], v[64:67]
	s_setprio 0
	s_barrier
	s_add_i32 s14, s16, s6
	v_lshl_add_u64 v[172:173], s[46:47], 0, v[152:153]
	s_mov_b32 m0, s14
	ds_read_b128 v[188:191], v178 offset:16384
	ds_read_b128 v[192:195], v178 offset:17408
	ds_read_b128 v[196:199], v178 offset:18432
	ds_read_b128 v[200:203], v178 offset:19456
	ds_read_b128 v[218:221], v178 offset:20480
	ds_read_b128 v[222:225], v178 offset:21504
	ds_read_b128 v[226:229], v178 offset:22528
	ds_read_b128 v[230:233], v178 offset:23552
	global_load_lds_dwordx4 v[172:173], off
	s_add_i32 m0, s14, 0x2000
	s_add_u32 s14, s46, 0x100000
	v_lshl_add_u64 v[204:205], s[46:47], 0, v[144:145]
	s_addc_u32 s15, s47, 0
	s_add_i32 s16, s17, s6
	global_load_lds_dwordx4 v[204:205], off
	s_waitcnt vmcnt(4)
	s_waitcnt lgkmcnt(0)
	s_barrier
; #define PG8_STAGE(bufoff, gbase, voff) do { _Pragma("unroll") for (int _i = 0; _i < 2; ++_i) \
;         __builtin_amdgcn_global_load_lds((const unsigned*)((const char*)(gbase) + (voff)[_i]), (LAS unsigned*)(lds + (bufoff) + ldsw + _i * 8192), 16, 0, 0); } while (0)
; #define PG8_LDA(dst, b, h) do { _Pragma("unroll") for (int m = 0; m < 4; ++m) _Pragma("unroll") for (int k = 0; k < 2; ++k) dst[m][k] = *(const LAS bf16x8*)(lds + PG8_SA(b, h) + aoff + m * 2048 + k * 1024); } while (0)
; #define PG8_LDB(dst, b, h) do { _Pragma("unroll") for (int n = 0; n < 2; ++n) _Pragma("unroll") for (int k = 0; k < 2; ++k) dst[n][k] = *(const LAS bf16x8*)(lds + PG8_SB(b, h) + boff + n * 2048 + k * 1024); } while (0)
; #define PG8_MMA(ai, bj, At, Bt) do { __builtin_amdgcn_s_setprio(1); _Pragma("unroll") for (int m = 0; m < 4; ++m) _Pragma("unroll") for (int n = 0; n < 2; ++n) _Pragma("unroll") for (int k = 0; k < 2; ++k) \
;         acc[ai][bj][m][n] = __builtin_amdgcn_mfma_f32_16x16x32_bf16(Bt[n][k], At[m][k], acc[ai][bj][m][n], 0, 0, 0); __builtin_amdgcn_s_setprio(0); } while (0)
; #define PG8_WAIT_V(n) asm volatile("s_waitcnt vmcnt(" #n ")" ::: "memory")
; #define PG8_WAIT_L(n) asm volatile("s_waitcnt lgkmcnt(" #n ")" ::: "memory")
; #define PG8_BAR __builtin_amdgcn_s_barrier()
; #define PG8_SCHED __builtin_amdgcn_sched_barrier(0)
; template <class Epi, class Sched, bool ALIGN_EPI = false, bool SP2 = false>
; __device__ __forceinline__ void gemm_phase(LAS unsigned char* lds, const Gemm g, const Sched& S, const Epi& E) {
;     ...
;             PG8_WAIT_V(8); PG8_WAIT_L(0); PG8_BAR; PG8_MMA(1, 0, At, B0); PG8_MMA(1, 1, At, B1); PG8_BAR; PG8_SCHED;
;             PG8_LDB(B0, 1, 0); PG8_LDB(B1, 1, 1); PG8_SCHED; PG8_LDA(At, 1, 0); PG8_STAGE(PG8_SA(0, 1), a2 + hstep, voffA);
;             PG8_WAIT_V(8); PG8_WAIT_L(0); PG8_BAR; PG8_MMA(0, 0, At, B0); PG8_MMA(0, 1, At, B1); PG8_BAR; PG8_SCHED;
	s_setprio 1
	s_waitcnt lgkmcnt(0)
	v_mfma_f32_16x16x32_bf16 v[60:63], v[128:131], v[188:191], v[60:63]
	v_mfma_f32_16x16x32_bf16 v[56:59], v[136:139], v[188:191], v[56:59]
	v_mfma_f32_16x16x32_bf16 v[44:47], v[128:131], v[196:199], v[44:47]
	v_lshl_add_u64 v[234:235], s[14:15], 0, v[152:153]
	s_mov_b32 m0, s16
	v_lshl_add_u64 v[236:237], s[48:49], 0, v[146:147]
	v_mfma_f32_16x16x32_bf16 v[40:43], v[136:139], v[196:199], v[40:43]
	global_load_lds_dwordx4 v[234:235], off
	v_mfma_f32_16x16x32_bf16 v[28:31], v[128:131], v[218:221], v[28:31]
	v_mfma_f32_16x16x32_bf16 v[24:27], v[136:139], v[218:221], v[24:27]
	v_mfma_f32_16x16x32_bf16 v[12:15], v[128:131], v[226:229], v[12:15]
	v_mfma_f32_16x16x32_bf16 v[8:11], v[136:139], v[226:229], v[8:11]
	v_mfma_f32_16x16x32_bf16 v[60:63], v[132:135], v[192:195], v[60:63]
	v_mfma_f32_16x16x32_bf16 v[56:59], v[140:143], v[192:195], v[56:59]
	v_lshl_add_u64 v[234:235], s[14:15], 0, v[144:145]
	s_add_i32 m0, s16, 0x2000
	v_mfma_f32_16x16x32_bf16 v[44:47], v[132:135], v[200:203], v[44:47]
	global_load_lds_dwordx4 v[234:235], off
	v_mfma_f32_16x16x32_bf16 v[40:43], v[140:143], v[200:203], v[40:43]
	v_mfma_f32_16x16x32_bf16 v[28:31], v[132:135], v[222:225], v[28:31]
	v_mfma_f32_16x16x32_bf16 v[24:27], v[140:143], v[222:225], v[24:27]
	v_mfma_f32_16x16x32_bf16 v[12:15], v[132:135], v[230:233], v[12:15]
	v_mfma_f32_16x16x32_bf16 v[8:11], v[140:143], v[230:233], v[8:11]
	s_setprio 0
	s_setprio 1
	v_mfma_f32_16x16x32_bf16 v[52:55], v[164:167], v[188:191], v[52:55]
	v_mfma_f32_16x16x32_bf16 v[48:51], v[180:183], v[188:191], v[48:51]
	v_lshl_add_u64 v[234:235], s[48:49], 0, v[148:149]
	s_mov_b32 m0, s7
	v_mfma_f32_16x16x32_bf16 v[36:39], v[164:167], v[196:199], v[36:39]
	global_load_lds_dwordx4 v[234:235], off
	v_mfma_f32_16x16x32_bf16 v[32:35], v[180:183], v[196:199], v[32:35]
	v_mfma_f32_16x16x32_bf16 v[20:23], v[164:167], v[218:221], v[20:23]
	v_mfma_f32_16x16x32_bf16 v[16:19], v[180:183], v[218:221], v[16:19]
	v_mfma_f32_16x16x32_bf16 v[4:7], v[164:167], v[226:229], v[4:7]
	v_mfma_f32_16x16x32_bf16 v[0:3], v[180:183], v[226:229], v[0:3]
	v_mfma_f32_16x16x32_bf16 v[52:55], v[168:171], v[192:195], v[52:55]
	v_mfma_f32_16x16x32_bf16 v[48:51], v[184:187], v[192:195], v[48:51]
	s_mov_b32 m0, s8
	v_mfma_f32_16x16x32_bf16 v[36:39], v[168:171], v[200:203], v[36:39]
	global_load_lds_dwordx4 v[236:237], off
	v_mfma_f32_16x16x32_bf16 v[32:35], v[184:187], v[200:203], v[32:35]
	v_mfma_f32_16x16x32_bf16 v[20:23], v[168:171], v[222:225], v[20:23]
	v_mfma_f32_16x16x32_bf16 v[16:19], v[184:187], v[222:225], v[16:19]
	v_mfma_f32_16x16x32_bf16 v[4:7], v[168:171], v[230:233], v[4:7]
	v_mfma_f32_16x16x32_bf16 v[0:3], v[184:187], v[230:233], v[0:3]
	s_setprio 0
	s_barrier
	s_add_i32 s16, 0, 0x18000
	s_add_i32 s17, 0, 0x1c000
	v_add_u32_e32 v140, s16, v175
	v_add_u32_e32 v179, s17, v175
	ds_read_b128 v[128:131], v140
	ds_read_b128 v[132:135], v140 offset:1024
	ds_read_b128 v[136:139], v140 offset:2048
	ds_read_b128 v[140:143], v140 offset:3072
	ds_read_b128 v[164:167], v179
	ds_read_b128 v[168:171], v179 offset:1024
	ds_read_b128 v[180:183], v179 offset:2048
	ds_read_b128 v[184:187], v179 offset:3072
	s_add_u32 s14, s48, 0x100000
	s_addc_u32 s15, s49, 0
	s_mov_b32 m0, s9
	v_lshl_add_u64 v[238:239], s[14:15], 0, v[148:149]
	ds_read_b128 v[188:191], v178 offset:32768
	ds_read_b128 v[192:195], v178 offset:33792
	ds_read_b128 v[196:199], v178 offset:34816
	ds_read_b128 v[200:203], v178 offset:35840
	ds_read_b128 v[218:221], v178 offset:36864
	ds_read_b128 v[222:225], v178 offset:37888
	ds_read_b128 v[226:229], v178 offset:38912
	ds_read_b128 v[230:233], v178 offset:39936
	global_load_lds_dwordx4 v[238:239], off
	v_lshl_add_u64 v[238:239], s[14:15], 0, v[146:147]
	s_mov_b32 m0, s10
	s_nop 0
	global_load_lds_dwordx4 v[238:239], off
	s_waitcnt vmcnt(8)
	s_waitcnt lgkmcnt(0)
	s_barrier
; #define PG8_STAGE(bufoff, gbase, voff) do { _Pragma("unroll") for (int _i = 0; _i < 2; ++_i) \
;         __builtin_amdgcn_global_load_lds((const unsigned*)((const char*)(gbase) + (voff)[_i]), (LAS unsigned*)(lds + (bufoff) + ldsw + _i * 8192), 16, 0, 0); } while (0)
; #define PG8_LDA(dst, b, h) do { _Pragma("unroll") for (int m = 0; m < 4; ++m) _Pragma("unroll") for (int k = 0; k < 2; ++k) dst[m][k] = *(const LAS bf16x8*)(lds + PG8_SA(b, h) + aoff + m * 2048 + k * 1024); } while (0)
; #define PG8_MMA(ai, bj, At, Bt) do { __builtin_amdgcn_s_setprio(1); _Pragma("unroll") for (int m = 0; m < 4; ++m) _Pragma("unroll") for (int n = 0; n < 2; ++n) _Pragma("unroll") for (int k = 0; k < 2; ++k) \
;         acc[ai][bj][m][n] = __builtin_amdgcn_mfma_f32_16x16x32_bf16(Bt[n][k], At[m][k], acc[ai][bj][m][n], 0, 0, 0); __builtin_amdgcn_s_setprio(0); } while (0)
; #define PG8_WAIT_V(n) asm volatile("s_waitcnt vmcnt(" #n ")" ::: "memory")
; #define PG8_WAIT_L(n) asm volatile("s_waitcnt lgkmcnt(" #n ")" ::: "memory")
; #define PG8_BAR __builtin_amdgcn_s_barrier()
; #define PG8_SCHED __builtin_amdgcn_sched_barrier(0)
; template <class Epi, class Sched, bool ALIGN_EPI = false, bool SP2 = false>
; __device__ __forceinline__ void gemm_phase(LAS unsigned char* lds, const Gemm g, const Sched& S, const Epi& E) {
;     ...
;         for (int t = 0; t < nt; t += 2) {
;     ...
;             PG8_WAIT_V(8); PG8_WAIT_L(0); PG8_BAR; PG8_MMA(0, 0, At, B0); PG8_MMA(0, 1, At, B1); PG8_BAR; PG8_SCHED;
;             PG8_LDA(At, 1, 1); PG8_STAGE(PG8_SB(1, 0), b3, voffB); PG8_STAGE(PG8_SB(1, 1), b3 + hstep, voffB); PG8_STAGE(PG8_SA(1, 0), a3, voffA);
;             PG8_WAIT_V(8); PG8_WAIT_L(0); PG8_BAR; PG8_MMA(1, 0, At, B0); PG8_MMA(1, 1, At, B1); PG8_BAR; PG8_SCHED;
	s_setprio 1
	s_waitcnt lgkmcnt(0)
	v_mfma_f32_16x16x32_bf16 v[124:127], v[128:131], v[188:191], v[124:127]
	v_mfma_f32_16x16x32_bf16 v[120:123], v[136:139], v[188:191], v[120:123]
	v_mfma_f32_16x16x32_bf16 v[112:115], v[128:131], v[196:199], v[112:115]
	v_mfma_f32_16x16x32_bf16 v[104:107], v[136:139], v[196:199], v[104:107]
	v_mfma_f32_16x16x32_bf16 v[92:95], v[128:131], v[218:221], v[92:95]
	v_mfma_f32_16x16x32_bf16 v[88:91], v[136:139], v[218:221], v[88:91]
	v_mfma_f32_16x16x32_bf16 v[76:79], v[128:131], v[226:229], v[76:79]
	v_mfma_f32_16x16x32_bf16 v[72:75], v[136:139], v[226:229], v[72:75]
	v_mfma_f32_16x16x32_bf16 v[124:127], v[132:135], v[192:195], v[124:127]
	v_mfma_f32_16x16x32_bf16 v[120:123], v[140:143], v[192:195], v[120:123]
	v_mfma_f32_16x16x32_bf16 v[112:115], v[132:135], v[200:203], v[112:115]
	v_mfma_f32_16x16x32_bf16 v[104:107], v[140:143], v[200:203], v[104:107]
	v_mfma_f32_16x16x32_bf16 v[92:95], v[132:135], v[222:225], v[92:95]
	v_mfma_f32_16x16x32_bf16 v[88:91], v[140:143], v[222:225], v[88:91]
	v_mfma_f32_16x16x32_bf16 v[76:79], v[132:135], v[230:233], v[76:79]
	v_mfma_f32_16x16x32_bf16 v[72:75], v[140:143], v[230:233], v[72:75]
	s_setprio 0
	s_setprio 1
	v_mfma_f32_16x16x32_bf16 v[116:119], v[164:167], v[188:191], v[116:119]
	v_mfma_f32_16x16x32_bf16 v[108:111], v[180:183], v[188:191], v[108:111]
	v_mfma_f32_16x16x32_bf16 v[100:103], v[164:167], v[196:199], v[100:103]
	v_mfma_f32_16x16x32_bf16 v[96:99], v[180:183], v[196:199], v[96:99]
	v_mfma_f32_16x16x32_bf16 v[84:87], v[164:167], v[218:221], v[84:87]
	v_mfma_f32_16x16x32_bf16 v[80:83], v[180:183], v[218:221], v[80:83]
	v_mfma_f32_16x16x32_bf16 v[68:71], v[164:167], v[226:229], v[68:71]
	v_mfma_f32_16x16x32_bf16 v[64:67], v[180:183], v[226:229], v[64:67]
	v_mfma_f32_16x16x32_bf16 v[116:119], v[168:171], v[192:195], v[116:119]
	v_mfma_f32_16x16x32_bf16 v[108:111], v[184:187], v[192:195], v[108:111]
	v_mfma_f32_16x16x32_bf16 v[100:103], v[168:171], v[200:203], v[100:103]
	v_mfma_f32_16x16x32_bf16 v[96:99], v[184:187], v[200:203], v[96:99]
	v_mfma_f32_16x16x32_bf16 v[84:87], v[168:171], v[222:225], v[84:87]
	v_mfma_f32_16x16x32_bf16 v[80:83], v[184:187], v[222:225], v[80:83]
	v_mfma_f32_16x16x32_bf16 v[68:71], v[168:171], v[230:233], v[68:71]
	v_mfma_f32_16x16x32_bf16 v[64:67], v[184:187], v[230:233], v[64:67]
	s_setprio 0
	s_barrier
	s_add_i32 s14, s16, s6
	v_lshl_add_u64 v[172:173], v[172:173], 0, s[30:31]
	s_mov_b32 m0, s14
	ds_read_b128 v[188:191], v178 offset:49152
	ds_read_b128 v[192:195], v178 offset:50176
	ds_read_b128 v[196:199], v178 offset:51200
	ds_read_b128 v[200:203], v178 offset:52224
	ds_read_b128 v[218:221], v178 offset:53248
	ds_read_b128 v[222:225], v178 offset:54272
	ds_read_b128 v[226:229], v178 offset:55296
	ds_read_b128 v[230:233], v178 offset:56320
	global_load_lds_dwordx4 v[172:173], off
	s_add_i32 m0, s14, 0x2000
	s_add_u32 s14, s46, 0x100080
	v_lshl_add_u64 v[172:173], v[204:205], 0, s[30:31]
	s_addc_u32 s15, s47, 0
	s_add_i32 s16, s17, s6
	global_load_lds_dwordx4 v[172:173], off
	s_waitcnt vmcnt(4)
	s_waitcnt lgkmcnt(0)
	s_barrier
	s_setprio 1
	s_waitcnt lgkmcnt(0)
	v_mfma_f32_16x16x32_bf16 v[60:63], v[128:131], v[188:191], v[60:63]
	v_mfma_f32_16x16x32_bf16 v[56:59], v[136:139], v[188:191], v[56:59]
	v_mfma_f32_16x16x32_bf16 v[44:47], v[128:131], v[196:199], v[44:47]
	v_lshl_add_u64 v[172:173], s[14:15], 0, v[152:153]
	s_mov_b32 m0, s16
	v_mfma_f32_16x16x32_bf16 v[40:43], v[136:139], v[196:199], v[40:43]
	global_load_lds_dwordx4 v[172:173], off
	v_mfma_f32_16x16x32_bf16 v[28:31], v[128:131], v[218:221], v[28:31]
	v_mfma_f32_16x16x32_bf16 v[24:27], v[136:139], v[218:221], v[24:27]
	v_mfma_f32_16x16x32_bf16 v[12:15], v[128:131], v[226:229], v[12:15]
	v_mfma_f32_16x16x32_bf16 v[8:11], v[136:139], v[226:229], v[8:11]
	v_mfma_f32_16x16x32_bf16 v[60:63], v[132:135], v[192:195], v[60:63]
	v_mfma_f32_16x16x32_bf16 v[56:59], v[140:143], v[192:195], v[56:59]
	v_lshl_add_u64 v[172:173], s[14:15], 0, v[144:145]
	s_add_i32 m0, s16, 0x2000
	v_mfma_f32_16x16x32_bf16 v[44:47], v[132:135], v[200:203], v[44:47]
	global_load_lds_dwordx4 v[172:173], off
	v_mfma_f32_16x16x32_bf16 v[40:43], v[140:143], v[200:203], v[40:43]
	v_mfma_f32_16x16x32_bf16 v[28:31], v[132:135], v[222:225], v[28:31]
	v_mfma_f32_16x16x32_bf16 v[24:27], v[140:143], v[222:225], v[24:27]
	v_mfma_f32_16x16x32_bf16 v[12:15], v[132:135], v[230:233], v[12:15]
	v_mfma_f32_16x16x32_bf16 v[8:11], v[140:143], v[230:233], v[8:11]
	s_setprio 0
	s_setprio 1
	v_mfma_f32_16x16x32_bf16 v[52:55], v[164:167], v[188:191], v[52:55]
	v_mfma_f32_16x16x32_bf16 v[48:51], v[180:183], v[188:191], v[48:51]
	v_lshl_add_u64 v[172:173], v[234:235], 0, s[30:31]
	s_mov_b32 m0, s12
	v_mfma_f32_16x16x32_bf16 v[36:39], v[164:167], v[196:199], v[36:39]
	global_load_lds_dwordx4 v[172:173], off
	v_mfma_f32_16x16x32_bf16 v[32:35], v[180:183], v[196:199], v[32:35]
	v_mfma_f32_16x16x32_bf16 v[20:23], v[164:167], v[218:221], v[20:23]
	v_mfma_f32_16x16x32_bf16 v[16:19], v[180:183], v[218:221], v[16:19]
	v_mfma_f32_16x16x32_bf16 v[4:7], v[164:167], v[226:229], v[4:7]
	v_mfma_f32_16x16x32_bf16 v[0:3], v[180:183], v[226:229], v[0:3]
	v_mfma_f32_16x16x32_bf16 v[52:55], v[168:171], v[192:195], v[52:55]
	v_mfma_f32_16x16x32_bf16 v[48:51], v[184:187], v[192:195], v[48:51]
	v_lshl_add_u64 v[172:173], v[236:237], 0, s[30:31]
	s_mov_b32 m0, s13
	v_mfma_f32_16x16x32_bf16 v[36:39], v[168:171], v[200:203], v[36:39]
	global_load_lds_dwordx4 v[172:173], off
	v_mfma_f32_16x16x32_bf16 v[32:35], v[184:187], v[200:203], v[32:35]
	v_mfma_f32_16x16x32_bf16 v[20:23], v[168:171], v[222:225], v[20:23]
	v_mfma_f32_16x16x32_bf16 v[16:19], v[184:187], v[222:225], v[16:19]
	v_mfma_f32_16x16x32_bf16 v[4:7], v[168:171], v[230:233], v[4:7]
	v_mfma_f32_16x16x32_bf16 v[0:3], v[184:187], v[230:233], v[0:3]
	s_setprio 0
	s_barrier
	s_add_i32 s71, s71, 2
	s_add_u32 s42, s42, 0x100
	s_addc_u32 s43, s43, 0
	s_add_u32 s64, s64, 0x100
	s_addc_u32 s65, s65, 0
	s_cmp_gt_u32 s71, 61
	s_cbranch_scc0 .LBB0_612
	s_and_b64 vcc, exec, s[26:27]
	s_cbranch_vccz .LBB0_615
	s_barrier
